# final LayerNorm fused into MLP-down GEMM epilogue: h2 tile kept in accumulators across last grid barrier, per-tile row stats via ws, no h2 store/reload
# speedup vs baseline: 1.0165x; 1.0165x over previous
;     __device__ __forceinline__ void operator()(const Acc& acc, const Unit& u, int wr, int wc, int fr, int fq) const {
;         const int col0 = u.pn * BM + wc * 32 + 4 * fq;
;         const float* gt = gate + (size_t)((u.pm * BM) >> 12) * NADA;
;         f32x4 gvv[2][2];
; #pragma unroll
;         for (int bj = 0; bj < 2; ++bj)
; #pragma unroll
;             for (int n = 0; n < 2; ++n) gvv[bj][n] = *(const f32x4*)(gt + col0 + bj * HALF + n * 16);
; #pragma unroll
;         for (int bj = 0; bj < 2; ++bj)
; #pragma unroll
;             for (int ai = 0; ai < 2; ++ai) {
;                 f32x4 bsv[4][2];
; #pragma unroll
;                 for (int m = 0; m < 4; ++m)
; #pragma unroll
;                     for (int n = 0; n < 2; ++n) { const size_t off = (size_t)(u.pm * BM + ai * HALF + wr * 64 + m * 16 + fr) * DMODEL + col0 + bj * HALF + n * 16; bsv[m][n] = __builtin_nontemporal_load((const f32x4*)(base + off)); }
; #pragma unroll
;                 for (int m = 0; m < 4; ++m)
; #pragma unroll
;                     for (int n = 0; n < 2; ++n) { const size_t off = (size_t)(u.pm * BM + ai * HALF + wr * 64 + m * 16 + fr) * DMODEL + col0 + bj * HALF + n * 16;
;                         *(f32x4*)(out + off) = bsv[m][n] * ALPHA + gvv[bj][n] * acc[ai][bj][m][n]; } }
; __global__ void __launch_bounds__(512, 2) fwd_kernel(Args a) {
;     ...
;             for (int j = 0; j < 8; ++j) { const f32x4 gg = ggv[j], bb = bbv[j];
;                 const f32x4 ya = va[j] * rstd_a * gg + bb, yb = vb[j] * rstd_b * gg + bb; __builtin_nontemporal_store(ya, xr + 64 * j); __builtin_nontemporal_store(yb, xr + 512 + 64 * j);
.LBB0_1102:
	v_lshl_or_b32 v64, s23, 8, v172
	s_ashr_i32 s15, s22, 4
	s_mul_hi_i32 s17, s15, 0xc000
	s_mul_i32 s15, s15, 0xc000
	v_ashrrev_i32_e32 v65, 31, v64
	v_lshl_add_u32 v168, s22, 8, v170
	s_add_u32 s24, s42, s15
	v_lshlrev_b64 v[164:165], 2, v[64:65]
	v_ashrrev_i32_e32 v169, 31, v168
	s_addc_u32 s25, s43, s17
	v_lshl_add_u64 v[166:167], s[4:5], 0, v[164:165]
	v_lshlrev_b64 v[210:211], 13, v[168:169]
	v_lshl_add_u64 v[64:65], s[24:25], 0, v[164:165]
	s_add_i32 s56, 0, 0x22068
	v_mov_b32_e32 v218, s56
	ds_read2_b64 v[218:221], v218 offset1:1
	s_add_i32 s56, 0, 0x220a0
	v_mov_b32_e32 v222, s56
	ds_read_b64 v[222:223], v222
	s_waitcnt lgkmcnt(0)
	v_readfirstlane_b32 s56, v218
	v_readfirstlane_b32 s57, v219
	v_readfirstlane_b32 s58, v220
	v_readfirstlane_b32 s59, v221
	v_readfirstlane_b32 s60, v222
	v_readfirstlane_b32 s61, v223
	s_add_u32 s60, s60, 0x210000
	s_addc_u32 s61, s61, 0
	v_lshl_add_u64 v[218:219], s[56:57], 0, v[164:165]
	v_lshl_add_u64 v[220:221], s[58:59], 0, v[164:165]
	global_load_dwordx4 v[224:227], v[218:219], off
	global_load_dwordx4 v[228:231], v[218:219], off offset:64
	global_load_dwordx4 v[232:235], v[218:219], off offset:512
	global_load_dwordx4 v[236:239], v[218:219], off offset:576
	global_load_dwordx4 v[240:243], v[220:221], off
	global_load_dwordx4 v[244:247], v[220:221], off offset:64
	global_load_dwordx4 v[248:251], v[220:221], off offset:512
	global_load_dwordx4 v[144:147], v[220:221], off offset:576
	v_lshlrev_b32_e32 v171, 3, v168
	global_load_dwordx2 v[148:149], v171, s[60:61]
	global_load_dwordx2 v[150:151], v171, s[60:61] offset:128
	global_load_dwordx2 v[152:153], v171, s[60:61] offset:256
	global_load_dwordx2 v[154:155], v171, s[60:61] offset:384
	global_load_dwordx2 v[252:253], v171, s[60:61] offset:1024
	global_load_dwordx2 v[174:175], v171, s[60:61] offset:1152
	global_load_dwordx2 v[222:223], v171, s[60:61] offset:1280
	global_load_dwordx2 v[220:221], v171, s[60:61] offset:1408
	v_lshl_add_u64 v[162:163], v[166:167], 0, v[210:211]
	global_load_dwordx4 v[140:143], v[64:65], off
	global_load_dwordx4 v[136:139], v[64:65], off offset:64
	global_load_dwordx4 v[68:71], v[64:65], off offset:512
	s_nop 0
	global_load_dwordx4 v[64:67], v[64:65], off offset:576
	s_nop 0
	global_load_dwordx4 v[176:179], v[162:163], off nt
	global_load_dwordx4 v[180:183], v[162:163], off offset:64 nt
	global_load_dwordx4 v[184:187], v[162:163], off offset:512 nt
	global_load_dwordx4 v[188:191], v[162:163], off offset:576 nt
	s_mov_b64 s[56:57], 0x20000
	v_lshl_add_u64 v[156:157], v[162:163], 0, s[56:57]
	global_load_dwordx4 v[198:201], v[156:157], off nt
	global_load_dwordx4 v[202:205], v[156:157], off offset:64 nt
	global_load_dwordx4 v[206:209], v[156:157], off offset:512 nt
	global_load_dwordx4 v[210:213], v[156:157], off offset:576 nt
	v_mov_b32_e32 v173, 0xba000000
	s_waitcnt vmcnt(4)
	v_pk_fma_f32 v[176:177], v[148:149], v[172:173], v[176:177] op_sel:[0,1,0] op_sel_hi:[0,1,1]
	v_pk_mul_f32 v[176:177], v[176:177], v[148:149] op_sel:[0,1] op_sel_hi:[1,1]
	v_pk_fma_f32 v[176:177], v[224:225], v[176:177], v[240:241]
	v_pk_mul_f32 v[176:177], v[176:177], s[12:13] op_sel_hi:[1,0]
	v_pk_fma_f32 v[132:133], v[132:133], v[140:141], v[176:177]
	v_pk_fma_f32 v[178:179], v[148:149], v[172:173], v[178:179] op_sel:[0,1,0] op_sel_hi:[0,1,1]
	v_pk_mul_f32 v[178:179], v[178:179], v[148:149] op_sel:[0,1] op_sel_hi:[1,1]
	v_pk_fma_f32 v[178:179], v[226:227], v[178:179], v[242:243]
	v_pk_mul_f32 v[178:179], v[178:179], s[12:13] op_sel_hi:[1,0]
	v_pk_fma_f32 v[134:135], v[134:135], v[142:143], v[178:179]
	v_pk_fma_f32 v[180:181], v[148:149], v[172:173], v[180:181] op_sel:[0,1,0] op_sel_hi:[0,1,1]
	v_pk_mul_f32 v[180:181], v[180:181], v[148:149] op_sel:[0,1] op_sel_hi:[1,1]
	v_pk_fma_f32 v[180:181], v[228:229], v[180:181], v[244:245]
	v_pk_mul_f32 v[180:181], v[180:181], s[12:13] op_sel_hi:[1,0]
	v_pk_fma_f32 v[128:129], v[128:129], v[136:137], v[180:181]
	v_pk_fma_f32 v[182:183], v[148:149], v[172:173], v[182:183] op_sel:[0,1,0] op_sel_hi:[0,1,1]
	v_pk_mul_f32 v[182:183], v[182:183], v[148:149] op_sel:[0,1] op_sel_hi:[1,1]
	v_pk_fma_f32 v[182:183], v[230:231], v[182:183], v[246:247]
	v_pk_mul_f32 v[182:183], v[182:183], s[12:13] op_sel_hi:[1,0]
	v_pk_fma_f32 v[130:131], v[130:131], v[138:139], v[182:183]
	v_pk_fma_f32 v[184:185], v[148:149], v[172:173], v[184:185] op_sel:[0,1,0] op_sel_hi:[0,1,1]
	v_pk_mul_f32 v[184:185], v[184:185], v[148:149] op_sel:[0,1] op_sel_hi:[1,1]
	v_pk_fma_f32 v[184:185], v[232:233], v[184:185], v[248:249]
	v_pk_mul_f32 v[184:185], v[184:185], s[12:13] op_sel_hi:[1,0]
	v_pk_fma_f32 v[60:61], v[60:61], v[68:69], v[184:185]
	v_pk_fma_f32 v[186:187], v[148:149], v[172:173], v[186:187] op_sel:[0,1,0] op_sel_hi:[0,1,1]
	v_pk_mul_f32 v[186:187], v[186:187], v[148:149] op_sel:[0,1] op_sel_hi:[1,1]
	v_pk_fma_f32 v[186:187], v[234:235], v[186:187], v[250:251]
	v_pk_mul_f32 v[186:187], v[186:187], s[12:13] op_sel_hi:[1,0]
	v_pk_fma_f32 v[62:63], v[62:63], v[70:71], v[186:187]
	v_pk_fma_f32 v[188:189], v[148:149], v[172:173], v[188:189] op_sel:[0,1,0] op_sel_hi:[0,1,1]
	v_pk_mul_f32 v[188:189], v[188:189], v[148:149] op_sel:[0,1] op_sel_hi:[1,1]
	v_pk_fma_f32 v[188:189], v[236:237], v[188:189], v[144:145]
	v_pk_mul_f32 v[188:189], v[188:189], s[12:13] op_sel_hi:[1,0]
	v_pk_fma_f32 v[56:57], v[56:57], v[64:65], v[188:189]
	v_pk_fma_f32 v[190:191], v[148:149], v[172:173], v[190:191] op_sel:[0,1,0] op_sel_hi:[0,1,1]
	v_pk_mul_f32 v[190:191], v[190:191], v[148:149] op_sel:[0,1] op_sel_hi:[1,1]
	v_pk_fma_f32 v[190:191], v[238:239], v[190:191], v[146:147]
	v_pk_mul_f32 v[190:191], v[190:191], s[12:13] op_sel_hi:[1,0]
	v_pk_fma_f32 v[58:59], v[58:59], v[66:67], v[190:191]
	s_mov_b64 s[56:57], 0x40000
	v_lshl_add_u64 v[156:157], v[162:163], 0, s[56:57]
	global_load_dwordx4 v[176:179], v[156:157], off nt
	global_load_dwordx4 v[180:183], v[156:157], off offset:64 nt
	global_load_dwordx4 v[184:187], v[156:157], off offset:512 nt
	global_load_dwordx4 v[188:191], v[156:157], off offset:576 nt
	s_waitcnt vmcnt(4)
;     __device__ __forceinline__ void operator()(const Acc& acc, const Unit& u, int wr, int wc, int fr, int fq) const {
;     ...
;                 for (int m = 0; m < 4; ++m)
; #pragma unroll
;                     for (int n = 0; n < 2; ++n) { const size_t off = (size_t)(u.pm * BM + ai * HALF + wr * 64 + m * 16 + fr) * DMODEL + col0 + bj * HALF + n * 16; bsv[m][n] = __builtin_nontemporal_load((const f32x4*)(base + off)); }
; #pragma unroll
;                 for (int m = 0; m < 4; ++m)
; #pragma unroll
;                     for (int n = 0; n < 2; ++n) { const size_t off = (size_t)(u.pm * BM + ai * HALF + wr * 64 + m * 16 + fr) * DMODEL + col0 + bj * HALF + n * 16;
;                         *(f32x4*)(out + off) = bsv[m][n] * ALPHA + gvv[bj][n] * acc[ai][bj][m][n]; } }
	v_pk_fma_f32 v[198:199], v[150:151], v[172:173], v[198:199] op_sel:[0,1,0] op_sel_hi:[0,1,1]
	v_pk_mul_f32 v[198:199], v[198:199], v[150:151] op_sel:[0,1] op_sel_hi:[1,1]
	v_pk_fma_f32 v[198:199], v[224:225], v[198:199], v[240:241]
	v_pk_mul_f32 v[198:199], v[198:199], s[12:13] op_sel_hi:[1,0]
	v_pk_fma_f32 v[124:125], v[124:125], v[140:141], v[198:199]
	v_pk_fma_f32 v[200:201], v[150:151], v[172:173], v[200:201] op_sel:[0,1,0] op_sel_hi:[0,1,1]
	v_pk_mul_f32 v[200:201], v[200:201], v[150:151] op_sel:[0,1] op_sel_hi:[1,1]
	v_pk_fma_f32 v[200:201], v[226:227], v[200:201], v[242:243]
	v_pk_mul_f32 v[200:201], v[200:201], s[12:13] op_sel_hi:[1,0]
	v_pk_fma_f32 v[126:127], v[126:127], v[142:143], v[200:201]
	v_pk_fma_f32 v[202:203], v[150:151], v[172:173], v[202:203] op_sel:[0,1,0] op_sel_hi:[0,1,1]
	v_pk_mul_f32 v[202:203], v[202:203], v[150:151] op_sel:[0,1] op_sel_hi:[1,1]
	v_pk_fma_f32 v[202:203], v[228:229], v[202:203], v[244:245]
	v_pk_mul_f32 v[202:203], v[202:203], s[12:13] op_sel_hi:[1,0]
	v_pk_fma_f32 v[120:121], v[120:121], v[136:137], v[202:203]
	v_pk_fma_f32 v[204:205], v[150:151], v[172:173], v[204:205] op_sel:[0,1,0] op_sel_hi:[0,1,1]
	v_pk_mul_f32 v[204:205], v[204:205], v[150:151] op_sel:[0,1] op_sel_hi:[1,1]
	v_pk_fma_f32 v[204:205], v[230:231], v[204:205], v[246:247]
	v_pk_mul_f32 v[204:205], v[204:205], s[12:13] op_sel_hi:[1,0]
	v_pk_fma_f32 v[122:123], v[122:123], v[138:139], v[204:205]
	v_pk_fma_f32 v[206:207], v[150:151], v[172:173], v[206:207] op_sel:[0,1,0] op_sel_hi:[0,1,1]
	v_pk_mul_f32 v[206:207], v[206:207], v[150:151] op_sel:[0,1] op_sel_hi:[1,1]
	v_pk_fma_f32 v[206:207], v[232:233], v[206:207], v[248:249]
	v_pk_mul_f32 v[206:207], v[206:207], s[12:13] op_sel_hi:[1,0]
	v_pk_fma_f32 v[52:53], v[52:53], v[68:69], v[206:207]
	v_pk_fma_f32 v[208:209], v[150:151], v[172:173], v[208:209] op_sel:[0,1,0] op_sel_hi:[0,1,1]
	v_pk_mul_f32 v[208:209], v[208:209], v[150:151] op_sel:[0,1] op_sel_hi:[1,1]
	v_pk_fma_f32 v[208:209], v[234:235], v[208:209], v[250:251]
	v_pk_mul_f32 v[208:209], v[208:209], s[12:13] op_sel_hi:[1,0]
	v_pk_fma_f32 v[54:55], v[54:55], v[70:71], v[208:209]
	v_pk_fma_f32 v[210:211], v[150:151], v[172:173], v[210:211] op_sel:[0,1,0] op_sel_hi:[0,1,1]
	v_pk_mul_f32 v[210:211], v[210:211], v[150:151] op_sel:[0,1] op_sel_hi:[1,1]
	v_pk_fma_f32 v[210:211], v[236:237], v[210:211], v[144:145]
	v_pk_mul_f32 v[210:211], v[210:211], s[12:13] op_sel_hi:[1,0]
	v_pk_fma_f32 v[48:49], v[48:49], v[64:65], v[210:211]
	v_pk_fma_f32 v[212:213], v[150:151], v[172:173], v[212:213] op_sel:[0,1,0] op_sel_hi:[0,1,1]
	v_pk_mul_f32 v[212:213], v[212:213], v[150:151] op_sel:[0,1] op_sel_hi:[1,1]
	v_pk_fma_f32 v[212:213], v[238:239], v[212:213], v[146:147]
	v_pk_mul_f32 v[212:213], v[212:213], s[12:13] op_sel_hi:[1,0]
	v_pk_fma_f32 v[50:51], v[50:51], v[66:67], v[212:213]
	s_mov_b64 s[56:57], 0x60000
	v_lshl_add_u64 v[156:157], v[162:163], 0, s[56:57]
	global_load_dwordx4 v[198:201], v[156:157], off nt
	global_load_dwordx4 v[202:205], v[156:157], off offset:64 nt
	global_load_dwordx4 v[206:209], v[156:157], off offset:512 nt
	global_load_dwordx4 v[210:213], v[156:157], off offset:576 nt
	s_waitcnt vmcnt(4)
	v_pk_fma_f32 v[176:177], v[152:153], v[172:173], v[176:177] op_sel:[0,1,0] op_sel_hi:[0,1,1]
	v_pk_mul_f32 v[176:177], v[176:177], v[152:153] op_sel:[0,1] op_sel_hi:[1,1]
	v_pk_fma_f32 v[176:177], v[224:225], v[176:177], v[240:241]
	v_pk_mul_f32 v[176:177], v[176:177], s[12:13] op_sel_hi:[1,0]
	v_pk_fma_f32 v[116:117], v[116:117], v[140:141], v[176:177]
	v_pk_fma_f32 v[178:179], v[152:153], v[172:173], v[178:179] op_sel:[0,1,0] op_sel_hi:[0,1,1]
	v_pk_mul_f32 v[178:179], v[178:179], v[152:153] op_sel:[0,1] op_sel_hi:[1,1]
	v_pk_fma_f32 v[178:179], v[226:227], v[178:179], v[242:243]
	v_pk_mul_f32 v[178:179], v[178:179], s[12:13] op_sel_hi:[1,0]
	v_pk_fma_f32 v[118:119], v[118:119], v[142:143], v[178:179]
	v_pk_fma_f32 v[180:181], v[152:153], v[172:173], v[180:181] op_sel:[0,1,0] op_sel_hi:[0,1,1]
	v_pk_mul_f32 v[180:181], v[180:181], v[152:153] op_sel:[0,1] op_sel_hi:[1,1]
	v_pk_fma_f32 v[180:181], v[228:229], v[180:181], v[244:245]
	v_pk_mul_f32 v[180:181], v[180:181], s[12:13] op_sel_hi:[1,0]
	v_pk_fma_f32 v[112:113], v[112:113], v[136:137], v[180:181]
	v_pk_fma_f32 v[182:183], v[152:153], v[172:173], v[182:183] op_sel:[0,1,0] op_sel_hi:[0,1,1]
	v_pk_mul_f32 v[182:183], v[182:183], v[152:153] op_sel:[0,1] op_sel_hi:[1,1]
	v_pk_fma_f32 v[182:183], v[230:231], v[182:183], v[246:247]
	v_pk_mul_f32 v[182:183], v[182:183], s[12:13] op_sel_hi:[1,0]
	v_pk_fma_f32 v[114:115], v[114:115], v[138:139], v[182:183]
	v_pk_fma_f32 v[184:185], v[152:153], v[172:173], v[184:185] op_sel:[0,1,0] op_sel_hi:[0,1,1]
	v_pk_mul_f32 v[184:185], v[184:185], v[152:153] op_sel:[0,1] op_sel_hi:[1,1]
	v_pk_fma_f32 v[184:185], v[232:233], v[184:185], v[248:249]
	v_pk_mul_f32 v[184:185], v[184:185], s[12:13] op_sel_hi:[1,0]
	v_pk_fma_f32 v[44:45], v[44:45], v[68:69], v[184:185]
	v_pk_fma_f32 v[186:187], v[152:153], v[172:173], v[186:187] op_sel:[0,1,0] op_sel_hi:[0,1,1]
	v_pk_mul_f32 v[186:187], v[186:187], v[152:153] op_sel:[0,1] op_sel_hi:[1,1]
	v_pk_fma_f32 v[186:187], v[234:235], v[186:187], v[250:251]
	v_pk_mul_f32 v[186:187], v[186:187], s[12:13] op_sel_hi:[1,0]
	v_pk_fma_f32 v[46:47], v[46:47], v[70:71], v[186:187]
	v_pk_fma_f32 v[188:189], v[152:153], v[172:173], v[188:189] op_sel:[0,1,0] op_sel_hi:[0,1,1]
	v_pk_mul_f32 v[188:189], v[188:189], v[152:153] op_sel:[0,1] op_sel_hi:[1,1]
	v_pk_fma_f32 v[188:189], v[236:237], v[188:189], v[144:145]
	v_pk_mul_f32 v[188:189], v[188:189], s[12:13] op_sel_hi:[1,0]
	v_pk_fma_f32 v[40:41], v[40:41], v[64:65], v[188:189]
	v_pk_fma_f32 v[190:191], v[152:153], v[172:173], v[190:191] op_sel:[0,1,0] op_sel_hi:[0,1,1]
	v_pk_mul_f32 v[190:191], v[190:191], v[152:153] op_sel:[0,1] op_sel_hi:[1,1]
	v_pk_fma_f32 v[190:191], v[238:239], v[190:191], v[146:147]
	v_pk_mul_f32 v[190:191], v[190:191], s[12:13] op_sel_hi:[1,0]
	v_pk_fma_f32 v[42:43], v[42:43], v[66:67], v[190:191]
	s_mov_b64 s[56:57], 0x100000
	v_lshl_add_u64 v[156:157], v[162:163], 0, s[56:57]
	global_load_dwordx4 v[176:179], v[156:157], off nt
	global_load_dwordx4 v[180:183], v[156:157], off offset:64 nt
	global_load_dwordx4 v[184:187], v[156:157], off offset:512 nt
	global_load_dwordx4 v[188:191], v[156:157], off offset:576 nt
	s_waitcnt vmcnt(4)
;     __device__ __forceinline__ void operator()(const Acc& acc, const Unit& u, int wr, int wc, int fr, int fq) const {
;     ...
;                 for (int m = 0; m < 4; ++m)
; #pragma unroll
;                     for (int n = 0; n < 2; ++n) { const size_t off = (size_t)(u.pm * BM + ai * HALF + wr * 64 + m * 16 + fr) * DMODEL + col0 + bj * HALF + n * 16; bsv[m][n] = __builtin_nontemporal_load((const f32x4*)(base + off)); }
; #pragma unroll
;                 for (int m = 0; m < 4; ++m)
; #pragma unroll
;                     for (int n = 0; n < 2; ++n) { const size_t off = (size_t)(u.pm * BM + ai * HALF + wr * 64 + m * 16 + fr) * DMODEL + col0 + bj * HALF + n * 16;
;                         *(f32x4*)(out + off) = bsv[m][n] * ALPHA + gvv[bj][n] * acc[ai][bj][m][n]; } }
	v_pk_fma_f32 v[198:199], v[154:155], v[172:173], v[198:199] op_sel:[0,1,0] op_sel_hi:[0,1,1]
	v_pk_mul_f32 v[198:199], v[198:199], v[154:155] op_sel:[0,1] op_sel_hi:[1,1]
	v_pk_fma_f32 v[198:199], v[224:225], v[198:199], v[240:241]
	v_pk_mul_f32 v[198:199], v[198:199], s[12:13] op_sel_hi:[1,0]
	v_pk_fma_f32 v[108:109], v[108:109], v[140:141], v[198:199]
	v_pk_fma_f32 v[200:201], v[154:155], v[172:173], v[200:201] op_sel:[0,1,0] op_sel_hi:[0,1,1]
	v_pk_mul_f32 v[200:201], v[200:201], v[154:155] op_sel:[0,1] op_sel_hi:[1,1]
	v_pk_fma_f32 v[200:201], v[226:227], v[200:201], v[242:243]
	v_pk_mul_f32 v[200:201], v[200:201], s[12:13] op_sel_hi:[1,0]
	v_pk_fma_f32 v[110:111], v[110:111], v[142:143], v[200:201]
	v_pk_fma_f32 v[202:203], v[154:155], v[172:173], v[202:203] op_sel:[0,1,0] op_sel_hi:[0,1,1]
	v_pk_mul_f32 v[202:203], v[202:203], v[154:155] op_sel:[0,1] op_sel_hi:[1,1]
	v_pk_fma_f32 v[202:203], v[228:229], v[202:203], v[244:245]
	v_pk_mul_f32 v[202:203], v[202:203], s[12:13] op_sel_hi:[1,0]
	v_pk_fma_f32 v[104:105], v[104:105], v[136:137], v[202:203]
	v_pk_fma_f32 v[204:205], v[154:155], v[172:173], v[204:205] op_sel:[0,1,0] op_sel_hi:[0,1,1]
	v_pk_mul_f32 v[204:205], v[204:205], v[154:155] op_sel:[0,1] op_sel_hi:[1,1]
	v_pk_fma_f32 v[204:205], v[230:231], v[204:205], v[246:247]
	v_pk_mul_f32 v[204:205], v[204:205], s[12:13] op_sel_hi:[1,0]
	v_pk_fma_f32 v[106:107], v[106:107], v[138:139], v[204:205]
	v_pk_fma_f32 v[206:207], v[154:155], v[172:173], v[206:207] op_sel:[0,1,0] op_sel_hi:[0,1,1]
	v_pk_mul_f32 v[206:207], v[206:207], v[154:155] op_sel:[0,1] op_sel_hi:[1,1]
	v_pk_fma_f32 v[206:207], v[232:233], v[206:207], v[248:249]
	v_pk_mul_f32 v[206:207], v[206:207], s[12:13] op_sel_hi:[1,0]
	v_pk_fma_f32 v[36:37], v[36:37], v[68:69], v[206:207]
	v_pk_fma_f32 v[208:209], v[154:155], v[172:173], v[208:209] op_sel:[0,1,0] op_sel_hi:[0,1,1]
	v_pk_mul_f32 v[208:209], v[208:209], v[154:155] op_sel:[0,1] op_sel_hi:[1,1]
	v_pk_fma_f32 v[208:209], v[234:235], v[208:209], v[250:251]
	v_pk_mul_f32 v[208:209], v[208:209], s[12:13] op_sel_hi:[1,0]
	v_pk_fma_f32 v[38:39], v[38:39], v[70:71], v[208:209]
	v_pk_fma_f32 v[210:211], v[154:155], v[172:173], v[210:211] op_sel:[0,1,0] op_sel_hi:[0,1,1]
	v_pk_mul_f32 v[210:211], v[210:211], v[154:155] op_sel:[0,1] op_sel_hi:[1,1]
	v_pk_fma_f32 v[210:211], v[236:237], v[210:211], v[144:145]
	v_pk_mul_f32 v[210:211], v[210:211], s[12:13] op_sel_hi:[1,0]
	v_pk_fma_f32 v[32:33], v[32:33], v[64:65], v[210:211]
	v_pk_fma_f32 v[212:213], v[154:155], v[172:173], v[212:213] op_sel:[0,1,0] op_sel_hi:[0,1,1]
	v_pk_mul_f32 v[212:213], v[212:213], v[154:155] op_sel:[0,1] op_sel_hi:[1,1]
	v_pk_fma_f32 v[212:213], v[238:239], v[212:213], v[146:147]
	v_pk_mul_f32 v[212:213], v[212:213], s[12:13] op_sel_hi:[1,0]
	v_pk_fma_f32 v[34:35], v[34:35], v[66:67], v[212:213]
	s_mov_b64 s[56:57], 0x120000
	v_lshl_add_u64 v[156:157], v[162:163], 0, s[56:57]
	global_load_dwordx4 v[198:201], v[156:157], off nt
	global_load_dwordx4 v[202:205], v[156:157], off offset:64 nt
	global_load_dwordx4 v[206:209], v[156:157], off offset:512 nt
	global_load_dwordx4 v[210:213], v[156:157], off offset:576 nt
	s_waitcnt vmcnt(4)
	v_pk_fma_f32 v[176:177], v[252:253], v[172:173], v[176:177] op_sel:[0,1,0] op_sel_hi:[0,1,1]
	v_pk_mul_f32 v[176:177], v[176:177], v[252:253] op_sel:[0,1] op_sel_hi:[1,1]
	v_pk_fma_f32 v[176:177], v[224:225], v[176:177], v[240:241]
	v_pk_mul_f32 v[176:177], v[176:177], s[12:13] op_sel_hi:[1,0]
	v_pk_fma_f32 v[100:101], v[100:101], v[140:141], v[176:177]
	v_pk_fma_f32 v[178:179], v[252:253], v[172:173], v[178:179] op_sel:[0,1,0] op_sel_hi:[0,1,1]
	v_pk_mul_f32 v[178:179], v[178:179], v[252:253] op_sel:[0,1] op_sel_hi:[1,1]
	v_pk_fma_f32 v[178:179], v[226:227], v[178:179], v[242:243]
	v_pk_mul_f32 v[178:179], v[178:179], s[12:13] op_sel_hi:[1,0]
	v_pk_fma_f32 v[102:103], v[102:103], v[142:143], v[178:179]
	v_pk_fma_f32 v[180:181], v[252:253], v[172:173], v[180:181] op_sel:[0,1,0] op_sel_hi:[0,1,1]
	v_pk_mul_f32 v[180:181], v[180:181], v[252:253] op_sel:[0,1] op_sel_hi:[1,1]
	v_pk_fma_f32 v[180:181], v[228:229], v[180:181], v[244:245]
	v_pk_mul_f32 v[180:181], v[180:181], s[12:13] op_sel_hi:[1,0]
	v_pk_fma_f32 v[96:97], v[96:97], v[136:137], v[180:181]
	v_pk_fma_f32 v[182:183], v[252:253], v[172:173], v[182:183] op_sel:[0,1,0] op_sel_hi:[0,1,1]
	v_pk_mul_f32 v[182:183], v[182:183], v[252:253] op_sel:[0,1] op_sel_hi:[1,1]
	v_pk_fma_f32 v[182:183], v[230:231], v[182:183], v[246:247]
	v_pk_mul_f32 v[182:183], v[182:183], s[12:13] op_sel_hi:[1,0]
	v_pk_fma_f32 v[98:99], v[98:99], v[138:139], v[182:183]
	v_pk_fma_f32 v[184:185], v[252:253], v[172:173], v[184:185] op_sel:[0,1,0] op_sel_hi:[0,1,1]
	v_pk_mul_f32 v[184:185], v[184:185], v[252:253] op_sel:[0,1] op_sel_hi:[1,1]
	v_pk_fma_f32 v[184:185], v[232:233], v[184:185], v[248:249]
	v_pk_mul_f32 v[184:185], v[184:185], s[12:13] op_sel_hi:[1,0]
	v_pk_fma_f32 v[28:29], v[28:29], v[68:69], v[184:185]
	v_pk_fma_f32 v[186:187], v[252:253], v[172:173], v[186:187] op_sel:[0,1,0] op_sel_hi:[0,1,1]
	v_pk_mul_f32 v[186:187], v[186:187], v[252:253] op_sel:[0,1] op_sel_hi:[1,1]
	v_pk_fma_f32 v[186:187], v[234:235], v[186:187], v[250:251]
	v_pk_mul_f32 v[186:187], v[186:187], s[12:13] op_sel_hi:[1,0]
	v_pk_fma_f32 v[30:31], v[30:31], v[70:71], v[186:187]
	v_pk_fma_f32 v[188:189], v[252:253], v[172:173], v[188:189] op_sel:[0,1,0] op_sel_hi:[0,1,1]
	v_pk_mul_f32 v[188:189], v[188:189], v[252:253] op_sel:[0,1] op_sel_hi:[1,1]
	v_pk_fma_f32 v[188:189], v[236:237], v[188:189], v[144:145]
	v_pk_mul_f32 v[188:189], v[188:189], s[12:13] op_sel_hi:[1,0]
	v_pk_fma_f32 v[24:25], v[24:25], v[64:65], v[188:189]
	v_pk_fma_f32 v[190:191], v[252:253], v[172:173], v[190:191] op_sel:[0,1,0] op_sel_hi:[0,1,1]
	v_pk_mul_f32 v[190:191], v[190:191], v[252:253] op_sel:[0,1] op_sel_hi:[1,1]
	v_pk_fma_f32 v[190:191], v[238:239], v[190:191], v[146:147]
	v_pk_mul_f32 v[190:191], v[190:191], s[12:13] op_sel_hi:[1,0]
	v_pk_fma_f32 v[26:27], v[26:27], v[66:67], v[190:191]
	s_mov_b64 s[56:57], 0x140000
	v_lshl_add_u64 v[156:157], v[162:163], 0, s[56:57]
	global_load_dwordx4 v[176:179], v[156:157], off nt
	global_load_dwordx4 v[180:183], v[156:157], off offset:64 nt
	global_load_dwordx4 v[184:187], v[156:157], off offset:512 nt
	global_load_dwordx4 v[188:191], v[156:157], off offset:576 nt
	s_waitcnt vmcnt(4)
;     __device__ __forceinline__ void operator()(const Acc& acc, const Unit& u, int wr, int wc, int fr, int fq) const {
;     ...
;                 for (int m = 0; m < 4; ++m)
; #pragma unroll
;                     for (int n = 0; n < 2; ++n) { const size_t off = (size_t)(u.pm * BM + ai * HALF + wr * 64 + m * 16 + fr) * DMODEL + col0 + bj * HALF + n * 16; bsv[m][n] = __builtin_nontemporal_load((const f32x4*)(base + off)); }
; #pragma unroll
;                 for (int m = 0; m < 4; ++m)
; #pragma unroll
;                     for (int n = 0; n < 2; ++n) { const size_t off = (size_t)(u.pm * BM + ai * HALF + wr * 64 + m * 16 + fr) * DMODEL + col0 + bj * HALF + n * 16;
;                         *(f32x4*)(out + off) = bsv[m][n] * ALPHA + gvv[bj][n] * acc[ai][bj][m][n]; } }
	v_pk_fma_f32 v[198:199], v[174:175], v[172:173], v[198:199] op_sel:[0,1,0] op_sel_hi:[0,1,1]
	v_pk_mul_f32 v[198:199], v[198:199], v[174:175] op_sel:[0,1] op_sel_hi:[1,1]
	v_pk_fma_f32 v[198:199], v[224:225], v[198:199], v[240:241]
	v_pk_mul_f32 v[198:199], v[198:199], s[12:13] op_sel_hi:[1,0]
	v_pk_fma_f32 v[92:93], v[92:93], v[140:141], v[198:199]
	v_pk_fma_f32 v[200:201], v[174:175], v[172:173], v[200:201] op_sel:[0,1,0] op_sel_hi:[0,1,1]
	v_pk_mul_f32 v[200:201], v[200:201], v[174:175] op_sel:[0,1] op_sel_hi:[1,1]
	v_pk_fma_f32 v[200:201], v[226:227], v[200:201], v[242:243]
	v_pk_mul_f32 v[200:201], v[200:201], s[12:13] op_sel_hi:[1,0]
	v_pk_fma_f32 v[94:95], v[94:95], v[142:143], v[200:201]
	v_pk_fma_f32 v[202:203], v[174:175], v[172:173], v[202:203] op_sel:[0,1,0] op_sel_hi:[0,1,1]
	v_pk_mul_f32 v[202:203], v[202:203], v[174:175] op_sel:[0,1] op_sel_hi:[1,1]
	v_pk_fma_f32 v[202:203], v[228:229], v[202:203], v[244:245]
	v_pk_mul_f32 v[202:203], v[202:203], s[12:13] op_sel_hi:[1,0]
	v_pk_fma_f32 v[88:89], v[88:89], v[136:137], v[202:203]
	v_pk_fma_f32 v[204:205], v[174:175], v[172:173], v[204:205] op_sel:[0,1,0] op_sel_hi:[0,1,1]
	v_pk_mul_f32 v[204:205], v[204:205], v[174:175] op_sel:[0,1] op_sel_hi:[1,1]
	v_pk_fma_f32 v[204:205], v[230:231], v[204:205], v[246:247]
	v_pk_mul_f32 v[204:205], v[204:205], s[12:13] op_sel_hi:[1,0]
	v_pk_fma_f32 v[90:91], v[90:91], v[138:139], v[204:205]
	v_pk_fma_f32 v[206:207], v[174:175], v[172:173], v[206:207] op_sel:[0,1,0] op_sel_hi:[0,1,1]
	v_pk_mul_f32 v[206:207], v[206:207], v[174:175] op_sel:[0,1] op_sel_hi:[1,1]
	v_pk_fma_f32 v[206:207], v[232:233], v[206:207], v[248:249]
	v_pk_mul_f32 v[206:207], v[206:207], s[12:13] op_sel_hi:[1,0]
	v_pk_fma_f32 v[20:21], v[20:21], v[68:69], v[206:207]
	v_pk_fma_f32 v[208:209], v[174:175], v[172:173], v[208:209] op_sel:[0,1,0] op_sel_hi:[0,1,1]
	v_pk_mul_f32 v[208:209], v[208:209], v[174:175] op_sel:[0,1] op_sel_hi:[1,1]
	v_pk_fma_f32 v[208:209], v[234:235], v[208:209], v[250:251]
	v_pk_mul_f32 v[208:209], v[208:209], s[12:13] op_sel_hi:[1,0]
	v_pk_fma_f32 v[22:23], v[22:23], v[70:71], v[208:209]
	v_pk_fma_f32 v[210:211], v[174:175], v[172:173], v[210:211] op_sel:[0,1,0] op_sel_hi:[0,1,1]
	v_pk_mul_f32 v[210:211], v[210:211], v[174:175] op_sel:[0,1] op_sel_hi:[1,1]
	v_pk_fma_f32 v[210:211], v[236:237], v[210:211], v[144:145]
	v_pk_mul_f32 v[210:211], v[210:211], s[12:13] op_sel_hi:[1,0]
	v_pk_fma_f32 v[16:17], v[16:17], v[64:65], v[210:211]
	v_pk_fma_f32 v[212:213], v[174:175], v[172:173], v[212:213] op_sel:[0,1,0] op_sel_hi:[0,1,1]
	v_pk_mul_f32 v[212:213], v[212:213], v[174:175] op_sel:[0,1] op_sel_hi:[1,1]
	v_pk_fma_f32 v[212:213], v[238:239], v[212:213], v[146:147]
	v_pk_mul_f32 v[212:213], v[212:213], s[12:13] op_sel_hi:[1,0]
	v_pk_fma_f32 v[18:19], v[18:19], v[66:67], v[212:213]
	s_mov_b64 s[56:57], 0x160000
	v_lshl_add_u64 v[156:157], v[162:163], 0, s[56:57]
	global_load_dwordx4 v[198:201], v[156:157], off nt
	global_load_dwordx4 v[202:205], v[156:157], off offset:64 nt
	global_load_dwordx4 v[206:209], v[156:157], off offset:512 nt
	global_load_dwordx4 v[210:213], v[156:157], off offset:576 nt
	s_waitcnt vmcnt(4)
	v_pk_fma_f32 v[176:177], v[222:223], v[172:173], v[176:177] op_sel:[0,1,0] op_sel_hi:[0,1,1]
	v_pk_mul_f32 v[176:177], v[176:177], v[222:223] op_sel:[0,1] op_sel_hi:[1,1]
	v_pk_fma_f32 v[176:177], v[224:225], v[176:177], v[240:241]
	v_pk_mul_f32 v[176:177], v[176:177], s[12:13] op_sel_hi:[1,0]
	v_pk_fma_f32 v[84:85], v[84:85], v[140:141], v[176:177]
	v_pk_fma_f32 v[178:179], v[222:223], v[172:173], v[178:179] op_sel:[0,1,0] op_sel_hi:[0,1,1]
	v_pk_mul_f32 v[178:179], v[178:179], v[222:223] op_sel:[0,1] op_sel_hi:[1,1]
	v_pk_fma_f32 v[178:179], v[226:227], v[178:179], v[242:243]
	v_pk_mul_f32 v[178:179], v[178:179], s[12:13] op_sel_hi:[1,0]
	v_pk_fma_f32 v[86:87], v[86:87], v[142:143], v[178:179]
	v_pk_fma_f32 v[180:181], v[222:223], v[172:173], v[180:181] op_sel:[0,1,0] op_sel_hi:[0,1,1]
	v_pk_mul_f32 v[180:181], v[180:181], v[222:223] op_sel:[0,1] op_sel_hi:[1,1]
	v_pk_fma_f32 v[180:181], v[228:229], v[180:181], v[244:245]
	v_pk_mul_f32 v[180:181], v[180:181], s[12:13] op_sel_hi:[1,0]
	v_pk_fma_f32 v[80:81], v[80:81], v[136:137], v[180:181]
	v_pk_fma_f32 v[182:183], v[222:223], v[172:173], v[182:183] op_sel:[0,1,0] op_sel_hi:[0,1,1]
	v_pk_mul_f32 v[182:183], v[182:183], v[222:223] op_sel:[0,1] op_sel_hi:[1,1]
	v_pk_fma_f32 v[182:183], v[230:231], v[182:183], v[246:247]
	v_pk_mul_f32 v[182:183], v[182:183], s[12:13] op_sel_hi:[1,0]
	v_pk_fma_f32 v[82:83], v[82:83], v[138:139], v[182:183]
	v_pk_fma_f32 v[184:185], v[222:223], v[172:173], v[184:185] op_sel:[0,1,0] op_sel_hi:[0,1,1]
	v_pk_mul_f32 v[184:185], v[184:185], v[222:223] op_sel:[0,1] op_sel_hi:[1,1]
	v_pk_fma_f32 v[184:185], v[232:233], v[184:185], v[248:249]
	v_pk_mul_f32 v[184:185], v[184:185], s[12:13] op_sel_hi:[1,0]
	v_pk_fma_f32 v[12:13], v[12:13], v[68:69], v[184:185]
	v_pk_fma_f32 v[186:187], v[222:223], v[172:173], v[186:187] op_sel:[0,1,0] op_sel_hi:[0,1,1]
	v_pk_mul_f32 v[186:187], v[186:187], v[222:223] op_sel:[0,1] op_sel_hi:[1,1]
	v_pk_fma_f32 v[186:187], v[234:235], v[186:187], v[250:251]
	v_pk_mul_f32 v[186:187], v[186:187], s[12:13] op_sel_hi:[1,0]
	v_pk_fma_f32 v[14:15], v[14:15], v[70:71], v[186:187]
	v_pk_fma_f32 v[188:189], v[222:223], v[172:173], v[188:189] op_sel:[0,1,0] op_sel_hi:[0,1,1]
	v_pk_mul_f32 v[188:189], v[188:189], v[222:223] op_sel:[0,1] op_sel_hi:[1,1]
	v_pk_fma_f32 v[188:189], v[236:237], v[188:189], v[144:145]
	v_pk_mul_f32 v[188:189], v[188:189], s[12:13] op_sel_hi:[1,0]
	v_pk_fma_f32 v[8:9], v[8:9], v[64:65], v[188:189]
	v_pk_fma_f32 v[190:191], v[222:223], v[172:173], v[190:191] op_sel:[0,1,0] op_sel_hi:[0,1,1]
	v_pk_mul_f32 v[190:191], v[190:191], v[222:223] op_sel:[0,1] op_sel_hi:[1,1]
	v_pk_fma_f32 v[190:191], v[238:239], v[190:191], v[146:147]
	v_pk_mul_f32 v[190:191], v[190:191], s[12:13] op_sel_hi:[1,0]
	v_pk_fma_f32 v[10:11], v[10:11], v[66:67], v[190:191]
	s_waitcnt vmcnt(0)
;     __device__ __forceinline__ void operator()(const Acc& acc, const Unit& u, int wr, int wc, int fr, int fq) const {
;     ...
;                 for (int m = 0; m < 4; ++m)
; #pragma unroll
;                     for (int n = 0; n < 2; ++n) { const size_t off = (size_t)(u.pm * BM + ai * HALF + wr * 64 + m * 16 + fr) * DMODEL + col0 + bj * HALF + n * 16; bsv[m][n] = __builtin_nontemporal_load((const f32x4*)(base + off)); }
; #pragma unroll
;                 for (int m = 0; m < 4; ++m)
; #pragma unroll
;                     for (int n = 0; n < 2; ++n) { const size_t off = (size_t)(u.pm * BM + ai * HALF + wr * 64 + m * 16 + fr) * DMODEL + col0 + bj * HALF + n * 16;
;                         *(f32x4*)(out + off) = bsv[m][n] * ALPHA + gvv[bj][n] * acc[ai][bj][m][n]; } }
; __global__ void __launch_bounds__(512, 2) fwd_kernel(Args a) {
;     ...
;             for (int q = 0; q < 4; ++q) { float s_ = 0.f;
; #pragma unroll
;                 for (int j = 0; j < 8; ++j) s_ += (vr[q][j][0] + vr[q][j][1]) + (vr[q][j][2] + vr[q][j][3]);
;                 sm[q] = wave_sum(s_) * (1.0f / DMODEL); }
	v_pk_fma_f32 v[198:199], v[220:221], v[172:173], v[198:199] op_sel:[0,1,0] op_sel_hi:[0,1,1]
	v_pk_mul_f32 v[198:199], v[198:199], v[220:221] op_sel:[0,1] op_sel_hi:[1,1]
	v_pk_fma_f32 v[198:199], v[224:225], v[198:199], v[240:241]
	v_pk_mul_f32 v[198:199], v[198:199], s[12:13] op_sel_hi:[1,0]
	v_pk_fma_f32 v[76:77], v[76:77], v[140:141], v[198:199]
	v_pk_fma_f32 v[200:201], v[220:221], v[172:173], v[200:201] op_sel:[0,1,0] op_sel_hi:[0,1,1]
	v_pk_mul_f32 v[200:201], v[200:201], v[220:221] op_sel:[0,1] op_sel_hi:[1,1]
	v_pk_fma_f32 v[200:201], v[226:227], v[200:201], v[242:243]
	v_pk_mul_f32 v[200:201], v[200:201], s[12:13] op_sel_hi:[1,0]
	v_pk_fma_f32 v[78:79], v[78:79], v[142:143], v[200:201]
	v_pk_fma_f32 v[202:203], v[220:221], v[172:173], v[202:203] op_sel:[0,1,0] op_sel_hi:[0,1,1]
	v_pk_mul_f32 v[202:203], v[202:203], v[220:221] op_sel:[0,1] op_sel_hi:[1,1]
	v_pk_fma_f32 v[202:203], v[228:229], v[202:203], v[244:245]
	v_pk_mul_f32 v[202:203], v[202:203], s[12:13] op_sel_hi:[1,0]
	v_pk_fma_f32 v[72:73], v[72:73], v[136:137], v[202:203]
	v_pk_fma_f32 v[204:205], v[220:221], v[172:173], v[204:205] op_sel:[0,1,0] op_sel_hi:[0,1,1]
	v_pk_mul_f32 v[204:205], v[204:205], v[220:221] op_sel:[0,1] op_sel_hi:[1,1]
	v_pk_fma_f32 v[204:205], v[230:231], v[204:205], v[246:247]
	v_pk_mul_f32 v[204:205], v[204:205], s[12:13] op_sel_hi:[1,0]
	v_pk_fma_f32 v[74:75], v[74:75], v[138:139], v[204:205]
	v_pk_fma_f32 v[206:207], v[220:221], v[172:173], v[206:207] op_sel:[0,1,0] op_sel_hi:[0,1,1]
	v_pk_mul_f32 v[206:207], v[206:207], v[220:221] op_sel:[0,1] op_sel_hi:[1,1]
	v_pk_fma_f32 v[206:207], v[232:233], v[206:207], v[248:249]
	v_pk_mul_f32 v[206:207], v[206:207], s[12:13] op_sel_hi:[1,0]
	v_pk_fma_f32 v[4:5], v[4:5], v[68:69], v[206:207]
	v_pk_fma_f32 v[208:209], v[220:221], v[172:173], v[208:209] op_sel:[0,1,0] op_sel_hi:[0,1,1]
	v_pk_mul_f32 v[208:209], v[208:209], v[220:221] op_sel:[0,1] op_sel_hi:[1,1]
	v_pk_fma_f32 v[208:209], v[234:235], v[208:209], v[250:251]
	v_pk_mul_f32 v[208:209], v[208:209], s[12:13] op_sel_hi:[1,0]
	v_pk_fma_f32 v[6:7], v[6:7], v[70:71], v[208:209]
	v_pk_fma_f32 v[210:211], v[220:221], v[172:173], v[210:211] op_sel:[0,1,0] op_sel_hi:[0,1,1]
	v_pk_mul_f32 v[210:211], v[210:211], v[220:221] op_sel:[0,1] op_sel_hi:[1,1]
	v_pk_fma_f32 v[210:211], v[236:237], v[210:211], v[144:145]
	v_pk_mul_f32 v[210:211], v[210:211], s[12:13] op_sel_hi:[1,0]
	v_pk_fma_f32 v[0:1], v[0:1], v[64:65], v[210:211]
	v_pk_fma_f32 v[212:213], v[220:221], v[172:173], v[212:213] op_sel:[0,1,0] op_sel_hi:[0,1,1]
	v_pk_mul_f32 v[212:213], v[212:213], v[220:221] op_sel:[0,1] op_sel_hi:[1,1]
	v_pk_fma_f32 v[212:213], v[238:239], v[212:213], v[146:147]
	v_pk_mul_f32 v[212:213], v[212:213], s[12:13] op_sel_hi:[1,0]
	v_pk_fma_f32 v[2:3], v[2:3], v[66:67], v[212:213]
	v_pk_add_f32 v[176:177], v[132:133], v[134:135]
	v_pk_add_f32 v[176:177], v[176:177], v[128:129]
	v_pk_add_f32 v[176:177], v[176:177], v[130:131]
	v_pk_add_f32 v[176:177], v[176:177], v[60:61]
	v_pk_add_f32 v[176:177], v[176:177], v[62:63]
	v_pk_add_f32 v[176:177], v[176:177], v[56:57]
	v_pk_add_f32 v[176:177], v[176:177], v[58:59]
	v_add_f32_e32 v224, v176, v177
	v_pk_add_f32 v[178:179], v[124:125], v[126:127]
	v_pk_add_f32 v[178:179], v[178:179], v[120:121]
	v_pk_add_f32 v[178:179], v[178:179], v[122:123]
	v_pk_add_f32 v[178:179], v[178:179], v[52:53]
	v_pk_add_f32 v[178:179], v[178:179], v[54:55]
	v_pk_add_f32 v[178:179], v[178:179], v[48:49]
	v_pk_add_f32 v[178:179], v[178:179], v[50:51]
	v_add_f32_e32 v225, v178, v179
	v_pk_add_f32 v[180:181], v[116:117], v[118:119]
	v_pk_add_f32 v[180:181], v[180:181], v[112:113]
	v_pk_add_f32 v[180:181], v[180:181], v[114:115]
	v_pk_add_f32 v[180:181], v[180:181], v[44:45]
	v_pk_add_f32 v[180:181], v[180:181], v[46:47]
	v_pk_add_f32 v[180:181], v[180:181], v[40:41]
	v_pk_add_f32 v[180:181], v[180:181], v[42:43]
	v_add_f32_e32 v226, v180, v181
	v_pk_add_f32 v[182:183], v[108:109], v[110:111]
	v_pk_add_f32 v[182:183], v[182:183], v[104:105]
	v_pk_add_f32 v[182:183], v[182:183], v[106:107]
	v_pk_add_f32 v[182:183], v[182:183], v[36:37]
	v_pk_add_f32 v[182:183], v[182:183], v[38:39]
	v_pk_add_f32 v[182:183], v[182:183], v[32:33]
	v_pk_add_f32 v[182:183], v[182:183], v[34:35]
	v_add_f32_e32 v227, v182, v183
	v_pk_add_f32 v[176:177], v[100:101], v[102:103]
	v_pk_add_f32 v[176:177], v[176:177], v[96:97]
	v_pk_add_f32 v[176:177], v[176:177], v[98:99]
	v_pk_add_f32 v[176:177], v[176:177], v[28:29]
	v_pk_add_f32 v[176:177], v[176:177], v[30:31]
	v_pk_add_f32 v[176:177], v[176:177], v[24:25]
	v_pk_add_f32 v[176:177], v[176:177], v[26:27]
	v_add_f32_e32 v228, v176, v177
	v_pk_add_f32 v[178:179], v[92:93], v[94:95]
	v_pk_add_f32 v[178:179], v[178:179], v[88:89]
	v_pk_add_f32 v[178:179], v[178:179], v[90:91]
	v_pk_add_f32 v[178:179], v[178:179], v[20:21]
	v_pk_add_f32 v[178:179], v[178:179], v[22:23]
	v_pk_add_f32 v[178:179], v[178:179], v[16:17]
	v_pk_add_f32 v[178:179], v[178:179], v[18:19]
	v_add_f32_e32 v229, v178, v179
	v_pk_add_f32 v[180:181], v[84:85], v[86:87]
	v_pk_add_f32 v[180:181], v[180:181], v[80:81]
	v_pk_add_f32 v[180:181], v[180:181], v[82:83]
	v_pk_add_f32 v[180:181], v[180:181], v[12:13]
	v_pk_add_f32 v[180:181], v[180:181], v[14:15]
	v_pk_add_f32 v[180:181], v[180:181], v[8:9]
	v_pk_add_f32 v[180:181], v[180:181], v[10:11]
	v_add_f32_e32 v230, v180, v181
	v_pk_add_f32 v[182:183], v[76:77], v[78:79]
	v_pk_add_f32 v[182:183], v[182:183], v[72:73]
	v_pk_add_f32 v[182:183], v[182:183], v[74:75]
	v_pk_add_f32 v[182:183], v[182:183], v[4:5]
	v_pk_add_f32 v[182:183], v[182:183], v[6:7]
	v_pk_add_f32 v[182:183], v[182:183], v[0:1]
; __global__ void __launch_bounds__(512, 2) fwd_kernel(Args a) {
;     ...
;             for (int q = 0; q < 4; ++q) { float s_ = 0.f;
; #pragma unroll
;                 for (int j = 0; j < 8; ++j) s_ += (vr[q][j][0] + vr[q][j][1]) + (vr[q][j][2] + vr[q][j][3]);
;                 sm[q] = wave_sum(s_) * (1.0f / DMODEL); }
; #pragma unroll
;             for (int q = 0; q < 4; ++q) { float s2 = 0.f;
; #pragma unroll
;                 for (int j = 0; j < 8; ++j) { vr[q][j] = vr[q][j] - sm[q]; s2 += (vr[q][j][0] * vr[q][j][0] + vr[q][j][1] * vr[q][j][1]) + (vr[q][j][2] * vr[q][j][2] + vr[q][j][3] * vr[q][j][3]); }
;                 qq[q] = wave_sum(s2); rs[q] = 1.0f / sqrtf(qq[q] * (1.0f / DMODEL) + LN_EPS); }
	v_pk_add_f32 v[182:183], v[182:183], v[2:3]
	v_add_f32_e32 v231, v182, v183
	v_mov_b32_e32 v198, v224
	v_mov_b32_e32 v206, v224
	v_mov_b32_e32 v199, v225
	v_mov_b32_e32 v207, v225
	v_mov_b32_e32 v200, v226
	v_mov_b32_e32 v208, v226
	v_mov_b32_e32 v201, v227
	v_mov_b32_e32 v209, v227
	v_mov_b32_e32 v202, v228
	v_mov_b32_e32 v210, v228
	v_mov_b32_e32 v203, v229
	v_mov_b32_e32 v211, v229
	v_mov_b32_e32 v204, v230
	v_mov_b32_e32 v212, v230
	v_mov_b32_e32 v205, v231
	v_mov_b32_e32 v213, v231
	s_nop 1
	v_permlane16_swap_b32_e32 v198, v206
	v_permlane16_swap_b32_e32 v199, v207
	v_permlane16_swap_b32_e32 v200, v208
	v_permlane16_swap_b32_e32 v201, v209
	v_permlane16_swap_b32_e32 v202, v210
	v_permlane16_swap_b32_e32 v203, v211
	v_permlane16_swap_b32_e32 v204, v212
	v_permlane16_swap_b32_e32 v205, v213
	s_nop 1
	v_add_f32_e32 v224, v198, v206
	v_add_f32_e32 v225, v199, v207
	v_add_f32_e32 v226, v200, v208
	v_add_f32_e32 v227, v201, v209
	v_add_f32_e32 v228, v202, v210
	v_add_f32_e32 v229, v203, v211
	v_add_f32_e32 v230, v204, v212
	v_add_f32_e32 v231, v205, v213
	v_mov_b32_e32 v198, v224
	v_mov_b32_e32 v206, v224
	v_mov_b32_e32 v199, v225
	v_mov_b32_e32 v207, v225
	v_mov_b32_e32 v200, v226
	v_mov_b32_e32 v208, v226
	v_mov_b32_e32 v201, v227
	v_mov_b32_e32 v209, v227
	v_mov_b32_e32 v202, v228
	v_mov_b32_e32 v210, v228
	v_mov_b32_e32 v203, v229
	v_mov_b32_e32 v211, v229
	v_mov_b32_e32 v204, v230
	v_mov_b32_e32 v212, v230
	v_mov_b32_e32 v205, v231
	v_mov_b32_e32 v213, v231
	s_nop 1
	v_permlane32_swap_b32_e32 v198, v206
	v_permlane32_swap_b32_e32 v199, v207
	v_permlane32_swap_b32_e32 v200, v208
	v_permlane32_swap_b32_e32 v201, v209
	v_permlane32_swap_b32_e32 v202, v210
	v_permlane32_swap_b32_e32 v203, v211
	v_permlane32_swap_b32_e32 v204, v212
	v_permlane32_swap_b32_e32 v205, v213
	s_nop 1
	v_add_f32_e32 v224, v198, v206
	v_add_f32_e32 v225, v199, v207
	v_add_f32_e32 v226, v200, v208
	v_add_f32_e32 v227, v201, v209
	v_add_f32_e32 v228, v202, v210
	v_add_f32_e32 v229, v203, v211
	v_add_f32_e32 v230, v204, v212
	v_add_f32_e32 v231, v205, v213
	s_and_b32 s56, s96, 3
	s_lshl_b32 s56, s56, 2
	v_lshl_add_u32 v214, v170, 4, s56
	v_lshlrev_b32_e32 v215, 4, v170
	s_waitcnt vmcnt(0) lgkmcnt(0)
	s_barrier
	ds_write_b32 v214, v224
	ds_write_b32 v214, v225 offset:256
	ds_write_b32 v214, v226 offset:512
	ds_write_b32 v214, v227 offset:768
	ds_write_b32 v214, v228 offset:2048
	ds_write_b32 v214, v229 offset:2304
	ds_write_b32 v214, v230 offset:2560
	ds_write_b32 v214, v231 offset:2816
	s_waitcnt lgkmcnt(0)
	s_barrier
	ds_read_b128 v[176:179], v215
	ds_read_b128 v[180:183], v215 offset:256
	ds_read_b128 v[184:187], v215 offset:512
	ds_read_b128 v[188:191], v215 offset:768
	ds_read_b128 v[198:201], v215 offset:2048
	ds_read_b128 v[202:205], v215 offset:2304
	ds_read_b128 v[206:209], v215 offset:2560
	ds_read_b128 v[210:213], v215 offset:2816
	s_waitcnt lgkmcnt(0)
	v_add_f32_e32 v144, v176, v177
	v_add_f32_e32 v144, v144, v178
	v_add_f32_e32 v144, v144, v179
	v_mul_f32_e32 v136, 0x3b800000, v144
	v_add_f32_e32 v146, v180, v181
	v_add_f32_e32 v146, v146, v182
	v_add_f32_e32 v146, v146, v183
	v_mul_f32_e32 v138, 0x3b800000, v146
	v_add_f32_e32 v148, v184, v185
	v_add_f32_e32 v148, v148, v186
	v_add_f32_e32 v148, v148, v187
	v_mul_f32_e32 v140, 0x3b800000, v148
	v_add_f32_e32 v150, v188, v189
	v_add_f32_e32 v150, v150, v190
	v_add_f32_e32 v150, v150, v191
	v_mul_f32_e32 v142, 0x3b800000, v150
	v_add_f32_e32 v152, v198, v199
	v_add_f32_e32 v152, v152, v200
	v_add_f32_e32 v152, v152, v201
	v_mul_f32_e32 v64, 0x3b800000, v152
	v_add_f32_e32 v154, v202, v203
	v_add_f32_e32 v154, v154, v204
	v_add_f32_e32 v154, v154, v205
	v_mul_f32_e32 v66, 0x3b800000, v154
	v_add_f32_e32 v156, v206, v207
	v_add_f32_e32 v156, v156, v208
	v_add_f32_e32 v156, v156, v209
	v_mul_f32_e32 v68, 0x3b800000, v156
	v_add_f32_e32 v158, v210, v211
	v_add_f32_e32 v158, v158, v212
	v_add_f32_e32 v158, v158, v213
	v_mul_f32_e32 v70, 0x3b800000, v158
	v_pk_add_f32 v[178:179], v[132:133], v[136:137] op_sel_hi:[1,0] neg_lo:[0,1] neg_hi:[0,1]
	v_pk_mul_f32 v[176:177], v[178:179], v[178:179]
	v_pk_add_f32 v[178:179], v[134:135], v[136:137] op_sel_hi:[1,0] neg_lo:[0,1] neg_hi:[0,1]
	v_pk_fma_f32 v[176:177], v[178:179], v[178:179], v[176:177]
	v_pk_add_f32 v[178:179], v[128:129], v[136:137] op_sel_hi:[1,0] neg_lo:[0,1] neg_hi:[0,1]
	v_pk_fma_f32 v[176:177], v[178:179], v[178:179], v[176:177]
	v_pk_add_f32 v[178:179], v[130:131], v[136:137] op_sel_hi:[1,0] neg_lo:[0,1] neg_hi:[0,1]
	v_pk_fma_f32 v[176:177], v[178:179], v[178:179], v[176:177]
	v_pk_add_f32 v[178:179], v[60:61], v[136:137] op_sel_hi:[1,0] neg_lo:[0,1] neg_hi:[0,1]
	v_pk_fma_f32 v[176:177], v[178:179], v[178:179], v[176:177]
	v_pk_add_f32 v[178:179], v[62:63], v[136:137] op_sel_hi:[1,0] neg_lo:[0,1] neg_hi:[0,1]
	v_pk_fma_f32 v[176:177], v[178:179], v[178:179], v[176:177]
	v_pk_add_f32 v[178:179], v[56:57], v[136:137] op_sel_hi:[1,0] neg_lo:[0,1] neg_hi:[0,1]
	v_pk_fma_f32 v[176:177], v[178:179], v[178:179], v[176:177]
	v_pk_add_f32 v[178:179], v[58:59], v[136:137] op_sel_hi:[1,0] neg_lo:[0,1] neg_hi:[0,1]
	v_pk_fma_f32 v[176:177], v[178:179], v[178:179], v[176:177]
	v_add_f32_e32 v224, v176, v177
	v_pk_add_f32 v[182:183], v[124:125], v[138:139] op_sel_hi:[1,0] neg_lo:[0,1] neg_hi:[0,1]
	v_pk_mul_f32 v[180:181], v[182:183], v[182:183]
	v_pk_add_f32 v[182:183], v[126:127], v[138:139] op_sel_hi:[1,0] neg_lo:[0,1] neg_hi:[0,1]
	v_pk_fma_f32 v[180:181], v[182:183], v[182:183], v[180:181]
	v_pk_add_f32 v[182:183], v[120:121], v[138:139] op_sel_hi:[1,0] neg_lo:[0,1] neg_hi:[0,1]
	v_pk_fma_f32 v[180:181], v[182:183], v[182:183], v[180:181]
; __global__ void __launch_bounds__(512, 2) fwd_kernel(Args a) {
;     ...
;             for (int q = 0; q < 4; ++q) { float s2 = 0.f;
; #pragma unroll
;                 for (int j = 0; j < 8; ++j) { vr[q][j] = vr[q][j] - sm[q]; s2 += (vr[q][j][0] * vr[q][j][0] + vr[q][j][1] * vr[q][j][1]) + (vr[q][j][2] * vr[q][j][2] + vr[q][j][3] * vr[q][j][3]); }
;                 qq[q] = wave_sum(s2); rs[q] = 1.0f / sqrtf(qq[q] * (1.0f / DMODEL) + LN_EPS); }
	v_pk_add_f32 v[182:183], v[122:123], v[138:139] op_sel_hi:[1,0] neg_lo:[0,1] neg_hi:[0,1]
	v_pk_fma_f32 v[180:181], v[182:183], v[182:183], v[180:181]
	v_pk_add_f32 v[182:183], v[52:53], v[138:139] op_sel_hi:[1,0] neg_lo:[0,1] neg_hi:[0,1]
	v_pk_fma_f32 v[180:181], v[182:183], v[182:183], v[180:181]
	v_pk_add_f32 v[182:183], v[54:55], v[138:139] op_sel_hi:[1,0] neg_lo:[0,1] neg_hi:[0,1]
	v_pk_fma_f32 v[180:181], v[182:183], v[182:183], v[180:181]
	v_pk_add_f32 v[182:183], v[48:49], v[138:139] op_sel_hi:[1,0] neg_lo:[0,1] neg_hi:[0,1]
	v_pk_fma_f32 v[180:181], v[182:183], v[182:183], v[180:181]
	v_pk_add_f32 v[182:183], v[50:51], v[138:139] op_sel_hi:[1,0] neg_lo:[0,1] neg_hi:[0,1]
	v_pk_fma_f32 v[180:181], v[182:183], v[182:183], v[180:181]
	v_add_f32_e32 v225, v180, v181
	v_pk_add_f32 v[186:187], v[116:117], v[140:141] op_sel_hi:[1,0] neg_lo:[0,1] neg_hi:[0,1]
	v_pk_mul_f32 v[184:185], v[186:187], v[186:187]
	v_pk_add_f32 v[186:187], v[118:119], v[140:141] op_sel_hi:[1,0] neg_lo:[0,1] neg_hi:[0,1]
	v_pk_fma_f32 v[184:185], v[186:187], v[186:187], v[184:185]
	v_pk_add_f32 v[186:187], v[112:113], v[140:141] op_sel_hi:[1,0] neg_lo:[0,1] neg_hi:[0,1]
	v_pk_fma_f32 v[184:185], v[186:187], v[186:187], v[184:185]
	v_pk_add_f32 v[186:187], v[114:115], v[140:141] op_sel_hi:[1,0] neg_lo:[0,1] neg_hi:[0,1]
	v_pk_fma_f32 v[184:185], v[186:187], v[186:187], v[184:185]
	v_pk_add_f32 v[186:187], v[44:45], v[140:141] op_sel_hi:[1,0] neg_lo:[0,1] neg_hi:[0,1]
	v_pk_fma_f32 v[184:185], v[186:187], v[186:187], v[184:185]
	v_pk_add_f32 v[186:187], v[46:47], v[140:141] op_sel_hi:[1,0] neg_lo:[0,1] neg_hi:[0,1]
	v_pk_fma_f32 v[184:185], v[186:187], v[186:187], v[184:185]
	v_pk_add_f32 v[186:187], v[40:41], v[140:141] op_sel_hi:[1,0] neg_lo:[0,1] neg_hi:[0,1]
	v_pk_fma_f32 v[184:185], v[186:187], v[186:187], v[184:185]
	v_pk_add_f32 v[186:187], v[42:43], v[140:141] op_sel_hi:[1,0] neg_lo:[0,1] neg_hi:[0,1]
	v_pk_fma_f32 v[184:185], v[186:187], v[186:187], v[184:185]
	v_add_f32_e32 v226, v184, v185
	v_pk_add_f32 v[190:191], v[108:109], v[142:143] op_sel_hi:[1,0] neg_lo:[0,1] neg_hi:[0,1]
	v_pk_mul_f32 v[188:189], v[190:191], v[190:191]
	v_pk_add_f32 v[190:191], v[110:111], v[142:143] op_sel_hi:[1,0] neg_lo:[0,1] neg_hi:[0,1]
	v_pk_fma_f32 v[188:189], v[190:191], v[190:191], v[188:189]
	v_pk_add_f32 v[190:191], v[104:105], v[142:143] op_sel_hi:[1,0] neg_lo:[0,1] neg_hi:[0,1]
	v_pk_fma_f32 v[188:189], v[190:191], v[190:191], v[188:189]
	v_pk_add_f32 v[190:191], v[106:107], v[142:143] op_sel_hi:[1,0] neg_lo:[0,1] neg_hi:[0,1]
	v_pk_fma_f32 v[188:189], v[190:191], v[190:191], v[188:189]
	v_pk_add_f32 v[190:191], v[36:37], v[142:143] op_sel_hi:[1,0] neg_lo:[0,1] neg_hi:[0,1]
	v_pk_fma_f32 v[188:189], v[190:191], v[190:191], v[188:189]
	v_pk_add_f32 v[190:191], v[38:39], v[142:143] op_sel_hi:[1,0] neg_lo:[0,1] neg_hi:[0,1]
	v_pk_fma_f32 v[188:189], v[190:191], v[190:191], v[188:189]
	v_pk_add_f32 v[190:191], v[32:33], v[142:143] op_sel_hi:[1,0] neg_lo:[0,1] neg_hi:[0,1]
	v_pk_fma_f32 v[188:189], v[190:191], v[190:191], v[188:189]
	v_pk_add_f32 v[190:191], v[34:35], v[142:143] op_sel_hi:[1,0] neg_lo:[0,1] neg_hi:[0,1]
	v_pk_fma_f32 v[188:189], v[190:191], v[190:191], v[188:189]
	v_add_f32_e32 v227, v188, v189
	v_pk_add_f32 v[178:179], v[100:101], v[64:65] op_sel_hi:[1,0] neg_lo:[0,1] neg_hi:[0,1]
	v_pk_mul_f32 v[176:177], v[178:179], v[178:179]
	v_pk_add_f32 v[178:179], v[102:103], v[64:65] op_sel_hi:[1,0] neg_lo:[0,1] neg_hi:[0,1]
	v_pk_fma_f32 v[176:177], v[178:179], v[178:179], v[176:177]
	v_pk_add_f32 v[178:179], v[96:97], v[64:65] op_sel_hi:[1,0] neg_lo:[0,1] neg_hi:[0,1]
	v_pk_fma_f32 v[176:177], v[178:179], v[178:179], v[176:177]
	v_pk_add_f32 v[178:179], v[98:99], v[64:65] op_sel_hi:[1,0] neg_lo:[0,1] neg_hi:[0,1]
	v_pk_fma_f32 v[176:177], v[178:179], v[178:179], v[176:177]
	v_pk_add_f32 v[178:179], v[28:29], v[64:65] op_sel_hi:[1,0] neg_lo:[0,1] neg_hi:[0,1]
	v_pk_fma_f32 v[176:177], v[178:179], v[178:179], v[176:177]
	v_pk_add_f32 v[178:179], v[30:31], v[64:65] op_sel_hi:[1,0] neg_lo:[0,1] neg_hi:[0,1]
	v_pk_fma_f32 v[176:177], v[178:179], v[178:179], v[176:177]
	v_pk_add_f32 v[178:179], v[24:25], v[64:65] op_sel_hi:[1,0] neg_lo:[0,1] neg_hi:[0,1]
	v_pk_fma_f32 v[176:177], v[178:179], v[178:179], v[176:177]
	v_pk_add_f32 v[178:179], v[26:27], v[64:65] op_sel_hi:[1,0] neg_lo:[0,1] neg_hi:[0,1]
	v_pk_fma_f32 v[176:177], v[178:179], v[178:179], v[176:177]
	v_add_f32_e32 v228, v176, v177
	v_pk_add_f32 v[182:183], v[92:93], v[66:67] op_sel_hi:[1,0] neg_lo:[0,1] neg_hi:[0,1]
	v_pk_mul_f32 v[180:181], v[182:183], v[182:183]
	v_pk_add_f32 v[182:183], v[94:95], v[66:67] op_sel_hi:[1,0] neg_lo:[0,1] neg_hi:[0,1]
	v_pk_fma_f32 v[180:181], v[182:183], v[182:183], v[180:181]
	v_pk_add_f32 v[182:183], v[88:89], v[66:67] op_sel_hi:[1,0] neg_lo:[0,1] neg_hi:[0,1]
	v_pk_fma_f32 v[180:181], v[182:183], v[182:183], v[180:181]
	v_pk_add_f32 v[182:183], v[90:91], v[66:67] op_sel_hi:[1,0] neg_lo:[0,1] neg_hi:[0,1]
	v_pk_fma_f32 v[180:181], v[182:183], v[182:183], v[180:181]
	v_pk_add_f32 v[182:183], v[20:21], v[66:67] op_sel_hi:[1,0] neg_lo:[0,1] neg_hi:[0,1]
	v_pk_fma_f32 v[180:181], v[182:183], v[182:183], v[180:181]
	v_pk_add_f32 v[182:183], v[22:23], v[66:67] op_sel_hi:[1,0] neg_lo:[0,1] neg_hi:[0,1]
	v_pk_fma_f32 v[180:181], v[182:183], v[182:183], v[180:181]
	v_pk_add_f32 v[182:183], v[16:17], v[66:67] op_sel_hi:[1,0] neg_lo:[0,1] neg_hi:[0,1]
	v_pk_fma_f32 v[180:181], v[182:183], v[182:183], v[180:181]
	v_pk_add_f32 v[182:183], v[18:19], v[66:67] op_sel_hi:[1,0] neg_lo:[0,1] neg_hi:[0,1]
	v_pk_fma_f32 v[180:181], v[182:183], v[182:183], v[180:181]
	v_add_f32_e32 v229, v180, v181
; __global__ void __launch_bounds__(512, 2) fwd_kernel(Args a) {
;     ...
;             for (int q = 0; q < 4; ++q) { float s2 = 0.f;
; #pragma unroll
;                 for (int j = 0; j < 8; ++j) { vr[q][j] = vr[q][j] - sm[q]; s2 += (vr[q][j][0] * vr[q][j][0] + vr[q][j][1] * vr[q][j][1]) + (vr[q][j][2] * vr[q][j][2] + vr[q][j][3] * vr[q][j][3]); }
;                 qq[q] = wave_sum(s2); rs[q] = 1.0f / sqrtf(qq[q] * (1.0f / DMODEL) + LN_EPS); }
	v_pk_add_f32 v[186:187], v[84:85], v[68:69] op_sel_hi:[1,0] neg_lo:[0,1] neg_hi:[0,1]
	v_pk_mul_f32 v[184:185], v[186:187], v[186:187]
	v_pk_add_f32 v[186:187], v[86:87], v[68:69] op_sel_hi:[1,0] neg_lo:[0,1] neg_hi:[0,1]
	v_pk_fma_f32 v[184:185], v[186:187], v[186:187], v[184:185]
	v_pk_add_f32 v[186:187], v[80:81], v[68:69] op_sel_hi:[1,0] neg_lo:[0,1] neg_hi:[0,1]
	v_pk_fma_f32 v[184:185], v[186:187], v[186:187], v[184:185]
	v_pk_add_f32 v[186:187], v[82:83], v[68:69] op_sel_hi:[1,0] neg_lo:[0,1] neg_hi:[0,1]
	v_pk_fma_f32 v[184:185], v[186:187], v[186:187], v[184:185]
	v_pk_add_f32 v[186:187], v[12:13], v[68:69] op_sel_hi:[1,0] neg_lo:[0,1] neg_hi:[0,1]
	v_pk_fma_f32 v[184:185], v[186:187], v[186:187], v[184:185]
	v_pk_add_f32 v[186:187], v[14:15], v[68:69] op_sel_hi:[1,0] neg_lo:[0,1] neg_hi:[0,1]
	v_pk_fma_f32 v[184:185], v[186:187], v[186:187], v[184:185]
	v_pk_add_f32 v[186:187], v[8:9], v[68:69] op_sel_hi:[1,0] neg_lo:[0,1] neg_hi:[0,1]
	v_pk_fma_f32 v[184:185], v[186:187], v[186:187], v[184:185]
	v_pk_add_f32 v[186:187], v[10:11], v[68:69] op_sel_hi:[1,0] neg_lo:[0,1] neg_hi:[0,1]
	v_pk_fma_f32 v[184:185], v[186:187], v[186:187], v[184:185]
	v_add_f32_e32 v230, v184, v185
	v_pk_add_f32 v[190:191], v[76:77], v[70:71] op_sel_hi:[1,0] neg_lo:[0,1] neg_hi:[0,1]
	v_pk_mul_f32 v[188:189], v[190:191], v[190:191]
	v_pk_add_f32 v[190:191], v[78:79], v[70:71] op_sel_hi:[1,0] neg_lo:[0,1] neg_hi:[0,1]
	v_pk_fma_f32 v[188:189], v[190:191], v[190:191], v[188:189]
	v_pk_add_f32 v[190:191], v[72:73], v[70:71] op_sel_hi:[1,0] neg_lo:[0,1] neg_hi:[0,1]
	v_pk_fma_f32 v[188:189], v[190:191], v[190:191], v[188:189]
	v_pk_add_f32 v[190:191], v[74:75], v[70:71] op_sel_hi:[1,0] neg_lo:[0,1] neg_hi:[0,1]
	v_pk_fma_f32 v[188:189], v[190:191], v[190:191], v[188:189]
	v_pk_add_f32 v[190:191], v[4:5], v[70:71] op_sel_hi:[1,0] neg_lo:[0,1] neg_hi:[0,1]
	v_pk_fma_f32 v[188:189], v[190:191], v[190:191], v[188:189]
	v_pk_add_f32 v[190:191], v[6:7], v[70:71] op_sel_hi:[1,0] neg_lo:[0,1] neg_hi:[0,1]
	v_pk_fma_f32 v[188:189], v[190:191], v[190:191], v[188:189]
	v_pk_add_f32 v[190:191], v[0:1], v[70:71] op_sel_hi:[1,0] neg_lo:[0,1] neg_hi:[0,1]
	v_pk_fma_f32 v[188:189], v[190:191], v[190:191], v[188:189]
	v_pk_add_f32 v[190:191], v[2:3], v[70:71] op_sel_hi:[1,0] neg_lo:[0,1] neg_hi:[0,1]
	v_pk_fma_f32 v[188:189], v[190:191], v[190:191], v[188:189]
	v_add_f32_e32 v231, v188, v189
	v_mov_b32_e32 v198, v224
	v_mov_b32_e32 v206, v224
	v_mov_b32_e32 v199, v225
	v_mov_b32_e32 v207, v225
	v_mov_b32_e32 v200, v226
	v_mov_b32_e32 v208, v226
	v_mov_b32_e32 v201, v227
	v_mov_b32_e32 v209, v227
	v_mov_b32_e32 v202, v228
	v_mov_b32_e32 v210, v228
	v_mov_b32_e32 v203, v229
	v_mov_b32_e32 v211, v229
	v_mov_b32_e32 v204, v230
	v_mov_b32_e32 v212, v230
	v_mov_b32_e32 v205, v231
	v_mov_b32_e32 v213, v231
	s_nop 1
	v_permlane16_swap_b32_e32 v198, v206
	v_permlane16_swap_b32_e32 v199, v207
	v_permlane16_swap_b32_e32 v200, v208
	v_permlane16_swap_b32_e32 v201, v209
	v_permlane16_swap_b32_e32 v202, v210
	v_permlane16_swap_b32_e32 v203, v211
	v_permlane16_swap_b32_e32 v204, v212
	v_permlane16_swap_b32_e32 v205, v213
	s_nop 1
	v_add_f32_e32 v224, v198, v206
	v_add_f32_e32 v225, v199, v207
	v_add_f32_e32 v226, v200, v208
	v_add_f32_e32 v227, v201, v209
	v_add_f32_e32 v228, v202, v210
	v_add_f32_e32 v229, v203, v211
	v_add_f32_e32 v230, v204, v212
	v_add_f32_e32 v231, v205, v213
	v_mov_b32_e32 v198, v224
	v_mov_b32_e32 v206, v224
	v_mov_b32_e32 v199, v225
	v_mov_b32_e32 v207, v225
	v_mov_b32_e32 v200, v226
	v_mov_b32_e32 v208, v226
	v_mov_b32_e32 v201, v227
	v_mov_b32_e32 v209, v227
	v_mov_b32_e32 v202, v228
	v_mov_b32_e32 v210, v228
	v_mov_b32_e32 v203, v229
	v_mov_b32_e32 v211, v229
	v_mov_b32_e32 v204, v230
	v_mov_b32_e32 v212, v230
	v_mov_b32_e32 v205, v231
	v_mov_b32_e32 v213, v231
	s_nop 1
	v_permlane32_swap_b32_e32 v198, v206
	v_permlane32_swap_b32_e32 v199, v207
	v_permlane32_swap_b32_e32 v200, v208
	v_permlane32_swap_b32_e32 v201, v209
	v_permlane32_swap_b32_e32 v202, v210
	v_permlane32_swap_b32_e32 v203, v211
	v_permlane32_swap_b32_e32 v204, v212
	v_permlane32_swap_b32_e32 v205, v213
	s_nop 1
	v_add_f32_e32 v224, v198, v206
	v_add_f32_e32 v225, v199, v207
	v_add_f32_e32 v226, v200, v208
	v_add_f32_e32 v227, v201, v209
	v_add_f32_e32 v228, v202, v210
	v_add_f32_e32 v229, v203, v211
	v_add_f32_e32 v230, v204, v212
	v_add_f32_e32 v231, v205, v213
	ds_write_b32 v214, v224 offset:4096
	ds_write_b32 v214, v225 offset:4352
	ds_write_b32 v214, v226 offset:4608
	ds_write_b32 v214, v227 offset:4864
	ds_write_b32 v214, v228 offset:6144
	ds_write_b32 v214, v229 offset:6400
	ds_write_b32 v214, v230 offset:6656
	ds_write_b32 v214, v231 offset:6912
	s_waitcnt lgkmcnt(0)
	s_barrier
	ds_read_b128 v[176:179], v215 offset:4096
	ds_read_b128 v[180:183], v215 offset:4352
	ds_read_b128 v[184:187], v215 offset:4608
	ds_read_b128 v[188:191], v215 offset:4864
	ds_read_b128 v[198:201], v215 offset:6144
	ds_read_b128 v[202:205], v215 offset:6400
	ds_read_b128 v[206:209], v215 offset:6656
	ds_read_b128 v[210:213], v215 offset:6912
	s_waitcnt lgkmcnt(0)
	v_add_f32_e32 v145, v176, v177
	v_add_f32_e32 v145, v145, v178
	v_add_f32_e32 v145, v145, v179
	v_add_f32_e32 v147, v180, v181
	v_add_f32_e32 v147, v147, v182
	v_add_f32_e32 v147, v147, v183
	v_add_f32_e32 v149, v184, v185
	v_add_f32_e32 v149, v149, v186
	v_add_f32_e32 v149, v149, v187
	v_add_f32_e32 v151, v188, v189
	v_add_f32_e32 v151, v151, v190
	v_add_f32_e32 v151, v151, v191
	v_add_f32_e32 v153, v198, v199
	v_add_f32_e32 v153, v153, v200
	v_add_f32_e32 v153, v153, v201
	v_add_f32_e32 v155, v202, v203
	v_add_f32_e32 v155, v155, v204
	v_add_f32_e32 v155, v155, v205
	v_add_f32_e32 v157, v206, v207
	v_add_f32_e32 v157, v157, v208
	v_add_f32_e32 v157, v157, v209
	v_add_f32_e32 v159, v210, v211
	v_add_f32_e32 v159, v159, v212
	v_add_f32_e32 v159, v159, v213
	s_and_b32 s56, s96, 3
	s_cmp_lg_u32 s56, 0
	s_cbranch_scc1 .Lln2_nostat
	s_mov_b64 s[58:59], exec
	s_mov_b64 exec, 0xffff
	v_lshlrev_b32_e32 v216, 6, v168
	v_lshrrev_b32_e32 v217, 10, v164
	v_lshl_add_u32 v216, v217, 3, v216
	v_add_u32_e32 v216, 0x10000, v216
	v_add_u32_e32 v217, 0x0, v216
	global_store_dwordx2 v217, v[144:145], s[60:61]
	v_add_u32_e32 v217, 0x400, v216
	global_store_dwordx2 v217, v[146:147], s[60:61]
	v_add_u32_e32 v217, 0x800, v216
	global_store_dwordx2 v217, v[148:149], s[60:61]
	v_add_u32_e32 v217, 0xc00, v216
	global_store_dwordx2 v217, v[150:151], s[60:61]
	v_add_u32_e32 v217, 0x2000, v216
	global_store_dwordx2 v217, v[152:153], s[60:61]
	v_add_u32_e32 v217, 0x2400, v216
	global_store_dwordx2 v217, v[154:155], s[60:61]
	v_add_u32_e32 v217, 0x2800, v216
	global_store_dwordx2 v217, v[156:157], s[60:61]
	v_add_u32_e32 v217, 0x2c00, v216
	global_store_dwordx2 v217, v[158:159], s[60:61]
	s_mov_b64 exec, s[58:59]
; #define PG8_BAR __builtin_amdgcn_s_barrier()
; template <class Epi, class Sched, bool ALIGN_EPI = true>
; __device__ __forceinline__ void gemm_phase(LAS unsigned char* lds, const Gemm g, const Sched& S, const Epi& E) {
;     ...
;         if (!has_next) break;
; #pragma unroll
;         for (int a = 0; a < 2; ++a)
; #pragma unroll
;             for (int b = 0; b < 2; ++b)
; #pragma unroll
;                 for (int m = 0; m < 4; ++m)
; #pragma unroll
;                     for (int n = 0; n < 2; ++n) acc[a][b][m][n] = (f32x4){0.f, 0.f, 0.f, 0.f};
;         cur = nxt; cA = nA; cB = nB; ++ui;
;         if constexpr (ALIGN_EPI) { if (wr == 1) PG8_BAR; }
;     }
.Lln2_nostat:
	v_mov_b32_e32 v176, v0
	v_mov_b32_e32 v177, v1
	v_mov_b32_e32 v178, v2
	v_mov_b32_e32 v179, v3
	v_mov_b32_e32 v180, v4
	v_mov_b32_e32 v181, v5
	v_mov_b32_e32 v182, v6
	v_mov_b32_e32 v183, v7
	v_mov_b32_e32 v184, v8
	v_mov_b32_e32 v185, v9
	v_mov_b32_e32 v186, v10
	v_mov_b32_e32 v187, v11
	v_mov_b32_e32 v188, v12
	v_mov_b32_e32 v189, v13
	v_mov_b32_e32 v190, v14
	v_mov_b32_e32 v191, v15
	v_mov_b32_e32 v192, v16
	v_mov_b32_e32 v193, v17
	v_mov_b32_e32 v194, v18
	v_mov_b32_e32 v195, v19
	s_mov_b64 s[22:23], -1
	s_andn2_b64 vcc, exec, s[2:3]
	s_cbranch_vccnz .LBB0_1091
	s_andn2_b64 vcc, exec, s[6:7]
	s_cbranch_vccnz .LBB0_1090
	s_barrier
	s_branch .LBB0_1090

; __global__ void __launch_bounds__(512, 2) fwd_kernel(Args a) {
;     ...
;     if (IN(12)) for (int rep = 0; rep < REPS(12); ++rep) { DECL_WS();
;         const float* const lng_p = IN_ln2_g; const float* const lnb_p = IN_ln2_b;
;         for (int m = 4 * gw; m < MTOK; m += 4 * NGW) { f32x4* xr = (f32x4*)(out + (size_t)m * DMODEL) + lane;
;             f32x4 vr[4][8]; float sm[4], qq[4], rs[4];
; #pragma unroll
;             for (int q = 0; q < 4; ++q)
; #pragma unroll
;                 for (int j = 0; j < 8; ++j) vr[q][j] = __builtin_nontemporal_load(xr + 512 * q + 64 * j);
;             f32x4 ggv[8], bbv[8];
; #pragma unroll
;             for (int j = 0; j < 8; ++j) { const int col = 4 * lane + 256 * j; ggv[j] = *(const f32x4*)(lng_p + col); bbv[j] = *(const f32x4*)(lnb_p + col); }
; #pragma unroll
;             for (int q = 0; q < 4; ++q) { float s_ = 0.f;
; #pragma unroll
;                 for (int j = 0; j < 8; ++j) s_ += (vr[q][j][0] + vr[q][j][1]) + (vr[q][j][2] + vr[q][j][3]);
;                 sm[q] = wave_sum(s_) * (1.0f / DMODEL); }
; #pragma unroll
;             for (int q = 0; q < 4; ++q) { float s2 = 0.f;
; #pragma unroll
;                 for (int j = 0; j < 8; ++j) { vr[q][j] = vr[q][j] - sm[q]; s2 += (vr[q][j][0] * vr[q][j][0] + vr[q][j][1] * vr[q][j][1]) + (vr[q][j][2] * vr[q][j][2] + vr[q][j][3] * vr[q][j][3]); }
;                 qq[q] = wave_sum(s2); rs[q] = 1.0f / sqrtf(qq[q] * (1.0f / DMODEL) + LN_EPS); }
; #pragma unroll
;             for (int q = 0; q < 4; ++q)
; #pragma unroll
;                 for (int j = 0; j < 8; ++j) __builtin_nontemporal_store(vr[q][j] * rs[q] * ggv[j] + bbv[j], xr + 512 * q + 64 * j); }
.LBB0_1156:
	s_cmp_lt_i32 s90, 13
	s_cselect_b64 s[0:1], -1, 0
	s_and_b64 s[0:1], s[0:1], s[2:3]
	s_andn2_b64 vcc, exec, s[0:1]
	s_cbranch_vccnz .LBB0_1160
	s_add_i32 s0, 0, 0x22098
	s_add_i32 s1, 0, 0x22088
	v_mov_b32_e32 v0, s0
	ds_read_b64 v[4:5], v0
	v_mov_b32_e32 v0, s1
	ds_read2_b64 v[0:3], v0 offset1:1
	s_cmpk_gt_i32 s96, 0x7ff
	s_waitcnt lgkmcnt(0)
	v_readfirstlane_b32 s3, v4
	v_readfirstlane_b32 s8, v5
	v_readfirstlane_b32 s0, v0
	v_readfirstlane_b32 s1, v1
	v_readfirstlane_b32 s6, v2
	v_readfirstlane_b32 s7, v3
	s_cbranch_scc1 .LBB0_1160
	s_add_i32 s2, 0, 0x220a0
	v_mov_b32_e32 v0, s2
	ds_read_b64 v[0:1], v0
	s_mov_b32 s4, s3
	s_mov_b32 s5, s8
	s_mov_b32 s3, 0xf800000
	s_mov_b32 s9, 0x3b800000
	v_lshl_add_u64 v[2:3], s[0:1], 0, v[164:165]
	v_lshl_add_u64 v[4:5], s[6:7], 0, v[164:165]
	global_load_dwordx4 v[224:227], v[2:3], off
	global_load_dwordx4 v[228:231], v[2:3], off offset:64
	global_load_dwordx4 v[232:235], v[2:3], off offset:512
	global_load_dwordx4 v[236:239], v[2:3], off offset:576
	global_load_dwordx4 v[136:139], v[4:5], off
	global_load_dwordx4 v[140:143], v[4:5], off offset:64
	global_load_dwordx4 v[144:147], v[4:5], off offset:512
	global_load_dwordx4 v[148:151], v[4:5], off offset:576
	s_waitcnt lgkmcnt(0)
	v_readfirstlane_b32 s10, v0
	v_readfirstlane_b32 s11, v1
	s_add_u32 s10, s10, 0x220000
	s_addc_u32 s11, s11, 0
	v_lshlrev_b32_e32 v154, 13, v168
	v_mov_b32_e32 v155, 0
	v_lshl_add_u64 v[152:153], s[4:5], 0, v[154:155]
	v_lshl_add_u64 v[152:153], v[152:153], 0, v[164:165]
	v_lshlrev_b32_e32 v156, 6, v168
	v_mov_b32_e32 v157, 0x3727c5ac
	v_mov_b32_e32 v158, 0x260
	v_add_u32_e32 v159, 0x0, v156
	global_load_dwordx4 v[198:201], v159, s[10:11]
	global_load_dwordx4 v[202:205], v159, s[10:11] offset:16
	global_load_dwordx4 v[206:209], v159, s[10:11] offset:32
	global_load_dwordx4 v[210:213], v159, s[10:11] offset:48
	v_add_u32_e32 v159, 0x400, v156
	global_load_dwordx4 v[0:3], v159, s[10:11]
	global_load_dwordx4 v[4:7], v159, s[10:11] offset:16
	global_load_dwordx4 v[8:11], v159, s[10:11] offset:32
	global_load_dwordx4 v[12:15], v159, s[10:11] offset:48
	s_waitcnt vmcnt(4)
	v_add_f32_e32 v16, v198, v200
	v_add_f32_e32 v16, v16, v202
	v_add_f32_e32 v16, v16, v204
	v_add_f32_e32 v16, v16, v206
	v_add_f32_e32 v16, v16, v208
	v_add_f32_e32 v16, v16, v210
	v_add_f32_e32 v16, v16, v212
	v_mul_f32_e32 v16, 0x3a000000, v16
	v_add_f32_e32 v17, v199, v201
	v_add_f32_e32 v17, v17, v203
	v_add_f32_e32 v17, v17, v205
	v_add_f32_e32 v17, v17, v207
	v_add_f32_e32 v17, v17, v209
	v_add_f32_e32 v17, v17, v211
	v_add_f32_e32 v17, v17, v213
	v_fma_f32 v18, v198, s9, -v16
	v_mul_f32_e32 v18, v18, v18
	v_fmac_f32_e32 v17, 0x43800000, v18
	v_fma_f32 v18, v200, s9, -v16
	v_mul_f32_e32 v18, v18, v18
	v_fmac_f32_e32 v17, 0x43800000, v18
	v_fma_f32 v18, v202, s9, -v16
	v_mul_f32_e32 v18, v18, v18
	v_fmac_f32_e32 v17, 0x43800000, v18
	v_fma_f32 v18, v204, s9, -v16
	v_mul_f32_e32 v18, v18, v18
	v_fmac_f32_e32 v17, 0x43800000, v18
	v_fma_f32 v18, v206, s9, -v16
	v_mul_f32_e32 v18, v18, v18
	v_fmac_f32_e32 v17, 0x43800000, v18
	v_fma_f32 v18, v208, s9, -v16
	v_mul_f32_e32 v18, v18, v18
	v_fmac_f32_e32 v17, 0x43800000, v18
	v_fma_f32 v18, v210, s9, -v16
	v_mul_f32_e32 v18, v18, v18
	v_fmac_f32_e32 v17, 0x43800000, v18
	v_fma_f32 v18, v212, s9, -v16
	v_mul_f32_e32 v18, v18, v18
	v_fmac_f32_e32 v17, 0x43800000, v18
	v_fmamk_f32 v17, v17, 0x3a000000, v157
	v_mul_f32_e32 v18, 0x4f800000, v17
	v_cmp_gt_f32_e32 vcc, s3, v17
	s_nop 1
	v_cndmask_b32_e32 v214, v17, v18, vcc
	v_sqrt_f32_e32 v215, v214
	s_nop 1
	v_add_u32_e32 v216, -1, v215
	v_fma_f32 v217, -v216, v215, v214
	v_cmp_ge_f32_e64 s[14:15], 0, v217
	v_add_u32_e32 v217, 1, v215
	v_fma_f32 v218, -v217, v215, v214
	s_nop 0
	v_cndmask_b32_e64 v216, v215, v216, s[14:15]
	v_cmp_lt_f32_e64 s[14:15], 0, v218
	s_nop 1
	v_cndmask_b32_e64 v216, v216, v217, s[14:15]
	v_mul_f32_e32 v217, 0x37800000, v216
	v_cndmask_b32_e32 v216, v216, v217, vcc
	v_cmp_class_f32_e32 vcc, v214, v158
	s_nop 1
	v_cndmask_b32_e32 v214, v216, v214, vcc
	v_div_scale_f32 v215, s[14:15], v214, v214, 1.0
	v_rcp_f32_e32 v216, v215
	s_nop 1
	v_fma_f32 v217, -v215, v216, 1.0
	v_fmac_f32_e32 v216, v217, v216
	v_div_scale_f32 v217, vcc, 1.0, v214, 1.0
	v_mul_f32_e32 v218, v217, v216
	v_fma_f32 v219, -v215, v218, v217
	v_fmac_f32_e32 v218, v219, v216
	v_fma_f32 v217, -v215, v218, v217
	s_nop 1
	v_div_fmas_f32 v215, v217, v216, v218
	v_div_fixup_f32 v214, v215, v214, 1.0
	s_mov_b64 s[12:13], 0x0
	v_lshl_add_u64 v[160:161], v[152:153], 0, s[12:13]
	v_pk_add_f32 v[132:133], v[132:133], v[16:17] op_sel_hi:[1,0] neg_lo:[0,1] neg_hi:[0,1]
	v_pk_mul_f32 v[132:133], v[132:133], v[214:215] op_sel_hi:[1,0]
	v_pk_fma_f32 v[132:133], v[224:225], v[132:133], v[136:137]
	v_pk_add_f32 v[134:135], v[134:135], v[16:17] op_sel_hi:[1,0] neg_lo:[0,1] neg_hi:[0,1]
	v_pk_mul_f32 v[134:135], v[134:135], v[214:215] op_sel_hi:[1,0]
	v_pk_fma_f32 v[134:135], v[226:227], v[134:135], v[138:139]
	global_store_dwordx4 v[160:161], v[132:135], off nt
	v_pk_add_f32 v[128:129], v[128:129], v[16:17] op_sel_hi:[1,0] neg_lo:[0,1] neg_hi:[0,1]
	v_pk_mul_f32 v[128:129], v[128:129], v[214:215] op_sel_hi:[1,0]
	v_pk_fma_f32 v[128:129], v[228:229], v[128:129], v[140:141]
	v_pk_add_f32 v[130:131], v[130:131], v[16:17] op_sel_hi:[1,0] neg_lo:[0,1] neg_hi:[0,1]
	v_pk_mul_f32 v[130:131], v[130:131], v[214:215] op_sel_hi:[1,0]
	v_pk_fma_f32 v[130:131], v[230:231], v[130:131], v[142:143]
	global_store_dwordx4 v[160:161], v[128:131], off offset:64 nt
	v_pk_add_f32 v[60:61], v[60:61], v[16:17] op_sel_hi:[1,0] neg_lo:[0,1] neg_hi:[0,1]
	v_pk_mul_f32 v[60:61], v[60:61], v[214:215] op_sel_hi:[1,0]
	v_pk_fma_f32 v[60:61], v[232:233], v[60:61], v[144:145]
	v_pk_add_f32 v[62:63], v[62:63], v[16:17] op_sel_hi:[1,0] neg_lo:[0,1] neg_hi:[0,1]
	v_pk_mul_f32 v[62:63], v[62:63], v[214:215] op_sel_hi:[1,0]
	v_pk_fma_f32 v[62:63], v[234:235], v[62:63], v[146:147]
	global_store_dwordx4 v[160:161], v[60:63], off offset:512 nt
	v_pk_add_f32 v[56:57], v[56:57], v[16:17] op_sel_hi:[1,0] neg_lo:[0,1] neg_hi:[0,1]
	v_pk_mul_f32 v[56:57], v[56:57], v[214:215] op_sel_hi:[1,0]
	v_pk_fma_f32 v[56:57], v[236:237], v[56:57], v[148:149]
	v_pk_add_f32 v[58:59], v[58:59], v[16:17] op_sel_hi:[1,0] neg_lo:[0,1] neg_hi:[0,1]
	v_pk_mul_f32 v[58:59], v[58:59], v[214:215] op_sel_hi:[1,0]
	v_pk_fma_f32 v[58:59], v[238:239], v[58:59], v[150:151]
	global_store_dwordx4 v[160:161], v[56:59], off offset:576 nt
	v_add_u32_e32 v159, 0x800, v156
	global_load_dwordx4 v[198:201], v159, s[10:11]
	global_load_dwordx4 v[202:205], v159, s[10:11] offset:16
	global_load_dwordx4 v[206:209], v159, s[10:11] offset:32
	global_load_dwordx4 v[210:213], v159, s[10:11] offset:48
	s_waitcnt vmcnt(8)
; __global__ void __launch_bounds__(512, 2) fwd_kernel(Args a) {
;     ...
;             for (int q = 0; q < 4; ++q) { float s2 = 0.f;
; #pragma unroll
;                 for (int j = 0; j < 8; ++j) { vr[q][j] = vr[q][j] - sm[q]; s2 += (vr[q][j][0] * vr[q][j][0] + vr[q][j][1] * vr[q][j][1]) + (vr[q][j][2] * vr[q][j][2] + vr[q][j][3] * vr[q][j][3]); }
;                 qq[q] = wave_sum(s2); rs[q] = 1.0f / sqrtf(qq[q] * (1.0f / DMODEL) + LN_EPS); }
; #pragma unroll
;             for (int q = 0; q < 4; ++q)
; #pragma unroll
;                 for (int j = 0; j < 8; ++j) __builtin_nontemporal_store(vr[q][j] * rs[q] * ggv[j] + bbv[j], xr + 512 * q + 64 * j); }
	v_add_f32_e32 v16, v0, v2
	v_add_f32_e32 v16, v16, v4
	v_add_f32_e32 v16, v16, v6
	v_add_f32_e32 v16, v16, v8
	v_add_f32_e32 v16, v16, v10
	v_add_f32_e32 v16, v16, v12
	v_add_f32_e32 v16, v16, v14
	v_mul_f32_e32 v16, 0x3a000000, v16
	v_add_f32_e32 v17, v1, v3
	v_add_f32_e32 v17, v17, v5
	v_add_f32_e32 v17, v17, v7
	v_add_f32_e32 v17, v17, v9
	v_add_f32_e32 v17, v17, v11
	v_add_f32_e32 v17, v17, v13
	v_add_f32_e32 v17, v17, v15
	v_fma_f32 v18, v0, s9, -v16
	v_mul_f32_e32 v18, v18, v18
	v_fmac_f32_e32 v17, 0x43800000, v18
	v_fma_f32 v18, v2, s9, -v16
	v_mul_f32_e32 v18, v18, v18
	v_fmac_f32_e32 v17, 0x43800000, v18
	v_fma_f32 v18, v4, s9, -v16
	v_mul_f32_e32 v18, v18, v18
	v_fmac_f32_e32 v17, 0x43800000, v18
	v_fma_f32 v18, v6, s9, -v16
	v_mul_f32_e32 v18, v18, v18
	v_fmac_f32_e32 v17, 0x43800000, v18
	v_fma_f32 v18, v8, s9, -v16
	v_mul_f32_e32 v18, v18, v18
	v_fmac_f32_e32 v17, 0x43800000, v18
	v_fma_f32 v18, v10, s9, -v16
	v_mul_f32_e32 v18, v18, v18
	v_fmac_f32_e32 v17, 0x43800000, v18
	v_fma_f32 v18, v12, s9, -v16
	v_mul_f32_e32 v18, v18, v18
	v_fmac_f32_e32 v17, 0x43800000, v18
	v_fma_f32 v18, v14, s9, -v16
	v_mul_f32_e32 v18, v18, v18
	v_fmac_f32_e32 v17, 0x43800000, v18
	v_fmamk_f32 v17, v17, 0x3a000000, v157
	v_mul_f32_e32 v18, 0x4f800000, v17
	v_cmp_gt_f32_e32 vcc, s3, v17
	s_nop 1
	v_cndmask_b32_e32 v214, v17, v18, vcc
	v_sqrt_f32_e32 v215, v214
	s_nop 1
	v_add_u32_e32 v216, -1, v215
	v_fma_f32 v217, -v216, v215, v214
	v_cmp_ge_f32_e64 s[14:15], 0, v217
	v_add_u32_e32 v217, 1, v215
	v_fma_f32 v218, -v217, v215, v214
	s_nop 0
	v_cndmask_b32_e64 v216, v215, v216, s[14:15]
	v_cmp_lt_f32_e64 s[14:15], 0, v218
	s_nop 1
	v_cndmask_b32_e64 v216, v216, v217, s[14:15]
	v_mul_f32_e32 v217, 0x37800000, v216
	v_cndmask_b32_e32 v216, v216, v217, vcc
	v_cmp_class_f32_e32 vcc, v214, v158
	s_nop 1
	v_cndmask_b32_e32 v214, v216, v214, vcc
	v_div_scale_f32 v215, s[14:15], v214, v214, 1.0
	v_rcp_f32_e32 v216, v215
	s_nop 1
	v_fma_f32 v217, -v215, v216, 1.0
	v_fmac_f32_e32 v216, v217, v216
	v_div_scale_f32 v217, vcc, 1.0, v214, 1.0
	v_mul_f32_e32 v218, v217, v216
	v_fma_f32 v219, -v215, v218, v217
	v_fmac_f32_e32 v218, v219, v216
	v_fma_f32 v217, -v215, v218, v217
	s_nop 1
	v_div_fmas_f32 v215, v217, v216, v218
	v_div_fixup_f32 v214, v215, v214, 1.0
	s_mov_b64 s[12:13], 0x20000
	v_lshl_add_u64 v[160:161], v[152:153], 0, s[12:13]
	v_pk_add_f32 v[124:125], v[124:125], v[16:17] op_sel_hi:[1,0] neg_lo:[0,1] neg_hi:[0,1]
	v_pk_mul_f32 v[124:125], v[124:125], v[214:215] op_sel_hi:[1,0]
	v_pk_fma_f32 v[124:125], v[224:225], v[124:125], v[136:137]
	v_pk_add_f32 v[126:127], v[126:127], v[16:17] op_sel_hi:[1,0] neg_lo:[0,1] neg_hi:[0,1]
	v_pk_mul_f32 v[126:127], v[126:127], v[214:215] op_sel_hi:[1,0]
	v_pk_fma_f32 v[126:127], v[226:227], v[126:127], v[138:139]
	global_store_dwordx4 v[160:161], v[124:127], off nt
	v_pk_add_f32 v[120:121], v[120:121], v[16:17] op_sel_hi:[1,0] neg_lo:[0,1] neg_hi:[0,1]
	v_pk_mul_f32 v[120:121], v[120:121], v[214:215] op_sel_hi:[1,0]
	v_pk_fma_f32 v[120:121], v[228:229], v[120:121], v[140:141]
	v_pk_add_f32 v[122:123], v[122:123], v[16:17] op_sel_hi:[1,0] neg_lo:[0,1] neg_hi:[0,1]
	v_pk_mul_f32 v[122:123], v[122:123], v[214:215] op_sel_hi:[1,0]
	v_pk_fma_f32 v[122:123], v[230:231], v[122:123], v[142:143]
	global_store_dwordx4 v[160:161], v[120:123], off offset:64 nt
	v_pk_add_f32 v[52:53], v[52:53], v[16:17] op_sel_hi:[1,0] neg_lo:[0,1] neg_hi:[0,1]
	v_pk_mul_f32 v[52:53], v[52:53], v[214:215] op_sel_hi:[1,0]
	v_pk_fma_f32 v[52:53], v[232:233], v[52:53], v[144:145]
	v_pk_add_f32 v[54:55], v[54:55], v[16:17] op_sel_hi:[1,0] neg_lo:[0,1] neg_hi:[0,1]
	v_pk_mul_f32 v[54:55], v[54:55], v[214:215] op_sel_hi:[1,0]
	v_pk_fma_f32 v[54:55], v[234:235], v[54:55], v[146:147]
	global_store_dwordx4 v[160:161], v[52:55], off offset:512 nt
	v_pk_add_f32 v[48:49], v[48:49], v[16:17] op_sel_hi:[1,0] neg_lo:[0,1] neg_hi:[0,1]
	v_pk_mul_f32 v[48:49], v[48:49], v[214:215] op_sel_hi:[1,0]
	v_pk_fma_f32 v[48:49], v[236:237], v[48:49], v[148:149]
	v_pk_add_f32 v[50:51], v[50:51], v[16:17] op_sel_hi:[1,0] neg_lo:[0,1] neg_hi:[0,1]
	v_pk_mul_f32 v[50:51], v[50:51], v[214:215] op_sel_hi:[1,0]
	v_pk_fma_f32 v[50:51], v[238:239], v[50:51], v[150:151]
	global_store_dwordx4 v[160:161], v[48:51], off offset:576 nt
	v_add_u32_e32 v159, 0xc00, v156
	global_load_dwordx4 v[0:3], v159, s[10:11]
	global_load_dwordx4 v[4:7], v159, s[10:11] offset:16
	global_load_dwordx4 v[8:11], v159, s[10:11] offset:32
	global_load_dwordx4 v[12:15], v159, s[10:11] offset:48
	s_waitcnt vmcnt(8)
; __global__ void __launch_bounds__(512, 2) fwd_kernel(Args a) {
;     ...
;             for (int q = 0; q < 4; ++q) { float s2 = 0.f;
; #pragma unroll
;                 for (int j = 0; j < 8; ++j) { vr[q][j] = vr[q][j] - sm[q]; s2 += (vr[q][j][0] * vr[q][j][0] + vr[q][j][1] * vr[q][j][1]) + (vr[q][j][2] * vr[q][j][2] + vr[q][j][3] * vr[q][j][3]); }
;                 qq[q] = wave_sum(s2); rs[q] = 1.0f / sqrtf(qq[q] * (1.0f / DMODEL) + LN_EPS); }
; #pragma unroll
;             for (int q = 0; q < 4; ++q)
; #pragma unroll
;                 for (int j = 0; j < 8; ++j) __builtin_nontemporal_store(vr[q][j] * rs[q] * ggv[j] + bbv[j], xr + 512 * q + 64 * j); }
	v_add_f32_e32 v16, v198, v200
	v_add_f32_e32 v16, v16, v202
	v_add_f32_e32 v16, v16, v204
	v_add_f32_e32 v16, v16, v206
	v_add_f32_e32 v16, v16, v208
	v_add_f32_e32 v16, v16, v210
	v_add_f32_e32 v16, v16, v212
	v_mul_f32_e32 v16, 0x3a000000, v16
	v_add_f32_e32 v17, v199, v201
	v_add_f32_e32 v17, v17, v203
	v_add_f32_e32 v17, v17, v205
	v_add_f32_e32 v17, v17, v207
	v_add_f32_e32 v17, v17, v209
	v_add_f32_e32 v17, v17, v211
	v_add_f32_e32 v17, v17, v213
	v_fma_f32 v18, v198, s9, -v16
	v_mul_f32_e32 v18, v18, v18
	v_fmac_f32_e32 v17, 0x43800000, v18
	v_fma_f32 v18, v200, s9, -v16
	v_mul_f32_e32 v18, v18, v18
	v_fmac_f32_e32 v17, 0x43800000, v18
	v_fma_f32 v18, v202, s9, -v16
	v_mul_f32_e32 v18, v18, v18
	v_fmac_f32_e32 v17, 0x43800000, v18
	v_fma_f32 v18, v204, s9, -v16
	v_mul_f32_e32 v18, v18, v18
	v_fmac_f32_e32 v17, 0x43800000, v18
	v_fma_f32 v18, v206, s9, -v16
	v_mul_f32_e32 v18, v18, v18
	v_fmac_f32_e32 v17, 0x43800000, v18
	v_fma_f32 v18, v208, s9, -v16
	v_mul_f32_e32 v18, v18, v18
	v_fmac_f32_e32 v17, 0x43800000, v18
	v_fma_f32 v18, v210, s9, -v16
	v_mul_f32_e32 v18, v18, v18
	v_fmac_f32_e32 v17, 0x43800000, v18
	v_fma_f32 v18, v212, s9, -v16
	v_mul_f32_e32 v18, v18, v18
	v_fmac_f32_e32 v17, 0x43800000, v18
	v_fmamk_f32 v17, v17, 0x3a000000, v157
	v_mul_f32_e32 v18, 0x4f800000, v17
	v_cmp_gt_f32_e32 vcc, s3, v17
	s_nop 1
	v_cndmask_b32_e32 v214, v17, v18, vcc
	v_sqrt_f32_e32 v215, v214
	s_nop 1
	v_add_u32_e32 v216, -1, v215
	v_fma_f32 v217, -v216, v215, v214
	v_cmp_ge_f32_e64 s[14:15], 0, v217
	v_add_u32_e32 v217, 1, v215
	v_fma_f32 v218, -v217, v215, v214
	s_nop 0
	v_cndmask_b32_e64 v216, v215, v216, s[14:15]
	v_cmp_lt_f32_e64 s[14:15], 0, v218
	s_nop 1
	v_cndmask_b32_e64 v216, v216, v217, s[14:15]
	v_mul_f32_e32 v217, 0x37800000, v216
	v_cndmask_b32_e32 v216, v216, v217, vcc
	v_cmp_class_f32_e32 vcc, v214, v158
	s_nop 1
	v_cndmask_b32_e32 v214, v216, v214, vcc
	v_div_scale_f32 v215, s[14:15], v214, v214, 1.0
	v_rcp_f32_e32 v216, v215
	s_nop 1
	v_fma_f32 v217, -v215, v216, 1.0
	v_fmac_f32_e32 v216, v217, v216
	v_div_scale_f32 v217, vcc, 1.0, v214, 1.0
	v_mul_f32_e32 v218, v217, v216
	v_fma_f32 v219, -v215, v218, v217
	v_fmac_f32_e32 v218, v219, v216
	v_fma_f32 v217, -v215, v218, v217
	s_nop 1
	v_div_fmas_f32 v215, v217, v216, v218
	v_div_fixup_f32 v214, v215, v214, 1.0
	s_mov_b64 s[12:13], 0x40000
	v_lshl_add_u64 v[160:161], v[152:153], 0, s[12:13]
	v_pk_add_f32 v[116:117], v[116:117], v[16:17] op_sel_hi:[1,0] neg_lo:[0,1] neg_hi:[0,1]
	v_pk_mul_f32 v[116:117], v[116:117], v[214:215] op_sel_hi:[1,0]
	v_pk_fma_f32 v[116:117], v[224:225], v[116:117], v[136:137]
	v_pk_add_f32 v[118:119], v[118:119], v[16:17] op_sel_hi:[1,0] neg_lo:[0,1] neg_hi:[0,1]
	v_pk_mul_f32 v[118:119], v[118:119], v[214:215] op_sel_hi:[1,0]
	v_pk_fma_f32 v[118:119], v[226:227], v[118:119], v[138:139]
	global_store_dwordx4 v[160:161], v[116:119], off nt
	v_pk_add_f32 v[112:113], v[112:113], v[16:17] op_sel_hi:[1,0] neg_lo:[0,1] neg_hi:[0,1]
	v_pk_mul_f32 v[112:113], v[112:113], v[214:215] op_sel_hi:[1,0]
	v_pk_fma_f32 v[112:113], v[228:229], v[112:113], v[140:141]
	v_pk_add_f32 v[114:115], v[114:115], v[16:17] op_sel_hi:[1,0] neg_lo:[0,1] neg_hi:[0,1]
	v_pk_mul_f32 v[114:115], v[114:115], v[214:215] op_sel_hi:[1,0]
	v_pk_fma_f32 v[114:115], v[230:231], v[114:115], v[142:143]
	global_store_dwordx4 v[160:161], v[112:115], off offset:64 nt
	v_pk_add_f32 v[44:45], v[44:45], v[16:17] op_sel_hi:[1,0] neg_lo:[0,1] neg_hi:[0,1]
	v_pk_mul_f32 v[44:45], v[44:45], v[214:215] op_sel_hi:[1,0]
	v_pk_fma_f32 v[44:45], v[232:233], v[44:45], v[144:145]
	v_pk_add_f32 v[46:47], v[46:47], v[16:17] op_sel_hi:[1,0] neg_lo:[0,1] neg_hi:[0,1]
	v_pk_mul_f32 v[46:47], v[46:47], v[214:215] op_sel_hi:[1,0]
	v_pk_fma_f32 v[46:47], v[234:235], v[46:47], v[146:147]
	global_store_dwordx4 v[160:161], v[44:47], off offset:512 nt
	v_pk_add_f32 v[40:41], v[40:41], v[16:17] op_sel_hi:[1,0] neg_lo:[0,1] neg_hi:[0,1]
	v_pk_mul_f32 v[40:41], v[40:41], v[214:215] op_sel_hi:[1,0]
	v_pk_fma_f32 v[40:41], v[236:237], v[40:41], v[148:149]
	v_pk_add_f32 v[42:43], v[42:43], v[16:17] op_sel_hi:[1,0] neg_lo:[0,1] neg_hi:[0,1]
	v_pk_mul_f32 v[42:43], v[42:43], v[214:215] op_sel_hi:[1,0]
	v_pk_fma_f32 v[42:43], v[238:239], v[42:43], v[150:151]
	global_store_dwordx4 v[160:161], v[40:43], off offset:576 nt
	v_add_u32_e32 v159, 0x2000, v156
	global_load_dwordx4 v[198:201], v159, s[10:11]
	global_load_dwordx4 v[202:205], v159, s[10:11] offset:16
	global_load_dwordx4 v[206:209], v159, s[10:11] offset:32
	global_load_dwordx4 v[210:213], v159, s[10:11] offset:48
	s_waitcnt vmcnt(8)
; __global__ void __launch_bounds__(512, 2) fwd_kernel(Args a) {
;     ...
;             for (int q = 0; q < 4; ++q) { float s2 = 0.f;
; #pragma unroll
;                 for (int j = 0; j < 8; ++j) { vr[q][j] = vr[q][j] - sm[q]; s2 += (vr[q][j][0] * vr[q][j][0] + vr[q][j][1] * vr[q][j][1]) + (vr[q][j][2] * vr[q][j][2] + vr[q][j][3] * vr[q][j][3]); }
;                 qq[q] = wave_sum(s2); rs[q] = 1.0f / sqrtf(qq[q] * (1.0f / DMODEL) + LN_EPS); }
; #pragma unroll
;             for (int q = 0; q < 4; ++q)
; #pragma unroll
;                 for (int j = 0; j < 8; ++j) __builtin_nontemporal_store(vr[q][j] * rs[q] * ggv[j] + bbv[j], xr + 512 * q + 64 * j); }
	v_add_f32_e32 v16, v0, v2
	v_add_f32_e32 v16, v16, v4
	v_add_f32_e32 v16, v16, v6
	v_add_f32_e32 v16, v16, v8
	v_add_f32_e32 v16, v16, v10
	v_add_f32_e32 v16, v16, v12
	v_add_f32_e32 v16, v16, v14
	v_mul_f32_e32 v16, 0x3a000000, v16
	v_add_f32_e32 v17, v1, v3
	v_add_f32_e32 v17, v17, v5
	v_add_f32_e32 v17, v17, v7
	v_add_f32_e32 v17, v17, v9
	v_add_f32_e32 v17, v17, v11
	v_add_f32_e32 v17, v17, v13
	v_add_f32_e32 v17, v17, v15
	v_fma_f32 v18, v0, s9, -v16
	v_mul_f32_e32 v18, v18, v18
	v_fmac_f32_e32 v17, 0x43800000, v18
	v_fma_f32 v18, v2, s9, -v16
	v_mul_f32_e32 v18, v18, v18
	v_fmac_f32_e32 v17, 0x43800000, v18
	v_fma_f32 v18, v4, s9, -v16
	v_mul_f32_e32 v18, v18, v18
	v_fmac_f32_e32 v17, 0x43800000, v18
	v_fma_f32 v18, v6, s9, -v16
	v_mul_f32_e32 v18, v18, v18
	v_fmac_f32_e32 v17, 0x43800000, v18
	v_fma_f32 v18, v8, s9, -v16
	v_mul_f32_e32 v18, v18, v18
	v_fmac_f32_e32 v17, 0x43800000, v18
	v_fma_f32 v18, v10, s9, -v16
	v_mul_f32_e32 v18, v18, v18
	v_fmac_f32_e32 v17, 0x43800000, v18
	v_fma_f32 v18, v12, s9, -v16
	v_mul_f32_e32 v18, v18, v18
	v_fmac_f32_e32 v17, 0x43800000, v18
	v_fma_f32 v18, v14, s9, -v16
	v_mul_f32_e32 v18, v18, v18
	v_fmac_f32_e32 v17, 0x43800000, v18
	v_fmamk_f32 v17, v17, 0x3a000000, v157
	v_mul_f32_e32 v18, 0x4f800000, v17
	v_cmp_gt_f32_e32 vcc, s3, v17
	s_nop 1
	v_cndmask_b32_e32 v214, v17, v18, vcc
	v_sqrt_f32_e32 v215, v214
	s_nop 1
	v_add_u32_e32 v216, -1, v215
	v_fma_f32 v217, -v216, v215, v214
	v_cmp_ge_f32_e64 s[14:15], 0, v217
	v_add_u32_e32 v217, 1, v215
	v_fma_f32 v218, -v217, v215, v214
	s_nop 0
	v_cndmask_b32_e64 v216, v215, v216, s[14:15]
	v_cmp_lt_f32_e64 s[14:15], 0, v218
	s_nop 1
	v_cndmask_b32_e64 v216, v216, v217, s[14:15]
	v_mul_f32_e32 v217, 0x37800000, v216
	v_cndmask_b32_e32 v216, v216, v217, vcc
	v_cmp_class_f32_e32 vcc, v214, v158
	s_nop 1
	v_cndmask_b32_e32 v214, v216, v214, vcc
	v_div_scale_f32 v215, s[14:15], v214, v214, 1.0
	v_rcp_f32_e32 v216, v215
	s_nop 1
	v_fma_f32 v217, -v215, v216, 1.0
	v_fmac_f32_e32 v216, v217, v216
	v_div_scale_f32 v217, vcc, 1.0, v214, 1.0
	v_mul_f32_e32 v218, v217, v216
	v_fma_f32 v219, -v215, v218, v217
	v_fmac_f32_e32 v218, v219, v216
	v_fma_f32 v217, -v215, v218, v217
	s_nop 1
	v_div_fmas_f32 v215, v217, v216, v218
	v_div_fixup_f32 v214, v215, v214, 1.0
	s_mov_b64 s[12:13], 0x60000
	v_lshl_add_u64 v[160:161], v[152:153], 0, s[12:13]
	v_pk_add_f32 v[108:109], v[108:109], v[16:17] op_sel_hi:[1,0] neg_lo:[0,1] neg_hi:[0,1]
	v_pk_mul_f32 v[108:109], v[108:109], v[214:215] op_sel_hi:[1,0]
	v_pk_fma_f32 v[108:109], v[224:225], v[108:109], v[136:137]
	v_pk_add_f32 v[110:111], v[110:111], v[16:17] op_sel_hi:[1,0] neg_lo:[0,1] neg_hi:[0,1]
	v_pk_mul_f32 v[110:111], v[110:111], v[214:215] op_sel_hi:[1,0]
	v_pk_fma_f32 v[110:111], v[226:227], v[110:111], v[138:139]
	global_store_dwordx4 v[160:161], v[108:111], off nt
	v_pk_add_f32 v[104:105], v[104:105], v[16:17] op_sel_hi:[1,0] neg_lo:[0,1] neg_hi:[0,1]
	v_pk_mul_f32 v[104:105], v[104:105], v[214:215] op_sel_hi:[1,0]
	v_pk_fma_f32 v[104:105], v[228:229], v[104:105], v[140:141]
	v_pk_add_f32 v[106:107], v[106:107], v[16:17] op_sel_hi:[1,0] neg_lo:[0,1] neg_hi:[0,1]
	v_pk_mul_f32 v[106:107], v[106:107], v[214:215] op_sel_hi:[1,0]
	v_pk_fma_f32 v[106:107], v[230:231], v[106:107], v[142:143]
	global_store_dwordx4 v[160:161], v[104:107], off offset:64 nt
	v_pk_add_f32 v[36:37], v[36:37], v[16:17] op_sel_hi:[1,0] neg_lo:[0,1] neg_hi:[0,1]
	v_pk_mul_f32 v[36:37], v[36:37], v[214:215] op_sel_hi:[1,0]
	v_pk_fma_f32 v[36:37], v[232:233], v[36:37], v[144:145]
	v_pk_add_f32 v[38:39], v[38:39], v[16:17] op_sel_hi:[1,0] neg_lo:[0,1] neg_hi:[0,1]
	v_pk_mul_f32 v[38:39], v[38:39], v[214:215] op_sel_hi:[1,0]
	v_pk_fma_f32 v[38:39], v[234:235], v[38:39], v[146:147]
	global_store_dwordx4 v[160:161], v[36:39], off offset:512 nt
	v_pk_add_f32 v[32:33], v[32:33], v[16:17] op_sel_hi:[1,0] neg_lo:[0,1] neg_hi:[0,1]
	v_pk_mul_f32 v[32:33], v[32:33], v[214:215] op_sel_hi:[1,0]
	v_pk_fma_f32 v[32:33], v[236:237], v[32:33], v[148:149]
	v_pk_add_f32 v[34:35], v[34:35], v[16:17] op_sel_hi:[1,0] neg_lo:[0,1] neg_hi:[0,1]
	v_pk_mul_f32 v[34:35], v[34:35], v[214:215] op_sel_hi:[1,0]
	v_pk_fma_f32 v[34:35], v[238:239], v[34:35], v[150:151]
	global_store_dwordx4 v[160:161], v[32:35], off offset:576 nt
	v_add_u32_e32 v159, 0x2400, v156
	global_load_dwordx4 v[0:3], v159, s[10:11]
	global_load_dwordx4 v[4:7], v159, s[10:11] offset:16
	global_load_dwordx4 v[8:11], v159, s[10:11] offset:32
	global_load_dwordx4 v[12:15], v159, s[10:11] offset:48
	s_waitcnt vmcnt(8)
; __global__ void __launch_bounds__(512, 2) fwd_kernel(Args a) {
;     ...
;             for (int q = 0; q < 4; ++q) { float s2 = 0.f;
; #pragma unroll
;                 for (int j = 0; j < 8; ++j) { vr[q][j] = vr[q][j] - sm[q]; s2 += (vr[q][j][0] * vr[q][j][0] + vr[q][j][1] * vr[q][j][1]) + (vr[q][j][2] * vr[q][j][2] + vr[q][j][3] * vr[q][j][3]); }
;                 qq[q] = wave_sum(s2); rs[q] = 1.0f / sqrtf(qq[q] * (1.0f / DMODEL) + LN_EPS); }
; #pragma unroll
;             for (int q = 0; q < 4; ++q)
; #pragma unroll
;                 for (int j = 0; j < 8; ++j) __builtin_nontemporal_store(vr[q][j] * rs[q] * ggv[j] + bbv[j], xr + 512 * q + 64 * j); }
	v_add_f32_e32 v16, v198, v200
	v_add_f32_e32 v16, v16, v202
	v_add_f32_e32 v16, v16, v204
	v_add_f32_e32 v16, v16, v206
	v_add_f32_e32 v16, v16, v208
	v_add_f32_e32 v16, v16, v210
	v_add_f32_e32 v16, v16, v212
	v_mul_f32_e32 v16, 0x3a000000, v16
	v_add_f32_e32 v17, v199, v201
	v_add_f32_e32 v17, v17, v203
	v_add_f32_e32 v17, v17, v205
	v_add_f32_e32 v17, v17, v207
	v_add_f32_e32 v17, v17, v209
	v_add_f32_e32 v17, v17, v211
	v_add_f32_e32 v17, v17, v213
	v_fma_f32 v18, v198, s9, -v16
	v_mul_f32_e32 v18, v18, v18
	v_fmac_f32_e32 v17, 0x43800000, v18
	v_fma_f32 v18, v200, s9, -v16
	v_mul_f32_e32 v18, v18, v18
	v_fmac_f32_e32 v17, 0x43800000, v18
	v_fma_f32 v18, v202, s9, -v16
	v_mul_f32_e32 v18, v18, v18
	v_fmac_f32_e32 v17, 0x43800000, v18
	v_fma_f32 v18, v204, s9, -v16
	v_mul_f32_e32 v18, v18, v18
	v_fmac_f32_e32 v17, 0x43800000, v18
	v_fma_f32 v18, v206, s9, -v16
	v_mul_f32_e32 v18, v18, v18
	v_fmac_f32_e32 v17, 0x43800000, v18
	v_fma_f32 v18, v208, s9, -v16
	v_mul_f32_e32 v18, v18, v18
	v_fmac_f32_e32 v17, 0x43800000, v18
	v_fma_f32 v18, v210, s9, -v16
	v_mul_f32_e32 v18, v18, v18
	v_fmac_f32_e32 v17, 0x43800000, v18
	v_fma_f32 v18, v212, s9, -v16
	v_mul_f32_e32 v18, v18, v18
	v_fmac_f32_e32 v17, 0x43800000, v18
	v_fmamk_f32 v17, v17, 0x3a000000, v157
	v_mul_f32_e32 v18, 0x4f800000, v17
	v_cmp_gt_f32_e32 vcc, s3, v17
	s_nop 1
	v_cndmask_b32_e32 v214, v17, v18, vcc
	v_sqrt_f32_e32 v215, v214
	s_nop 1
	v_add_u32_e32 v216, -1, v215
	v_fma_f32 v217, -v216, v215, v214
	v_cmp_ge_f32_e64 s[14:15], 0, v217
	v_add_u32_e32 v217, 1, v215
	v_fma_f32 v218, -v217, v215, v214
	s_nop 0
	v_cndmask_b32_e64 v216, v215, v216, s[14:15]
	v_cmp_lt_f32_e64 s[14:15], 0, v218
	s_nop 1
	v_cndmask_b32_e64 v216, v216, v217, s[14:15]
	v_mul_f32_e32 v217, 0x37800000, v216
	v_cndmask_b32_e32 v216, v216, v217, vcc
	v_cmp_class_f32_e32 vcc, v214, v158
	s_nop 1
	v_cndmask_b32_e32 v214, v216, v214, vcc
	v_div_scale_f32 v215, s[14:15], v214, v214, 1.0
	v_rcp_f32_e32 v216, v215
	s_nop 1
	v_fma_f32 v217, -v215, v216, 1.0
	v_fmac_f32_e32 v216, v217, v216
	v_div_scale_f32 v217, vcc, 1.0, v214, 1.0
	v_mul_f32_e32 v218, v217, v216
	v_fma_f32 v219, -v215, v218, v217
	v_fmac_f32_e32 v218, v219, v216
	v_fma_f32 v217, -v215, v218, v217
	s_nop 1
	v_div_fmas_f32 v215, v217, v216, v218
	v_div_fixup_f32 v214, v215, v214, 1.0
	s_mov_b64 s[12:13], 0x100000
	v_lshl_add_u64 v[160:161], v[152:153], 0, s[12:13]
	v_pk_add_f32 v[100:101], v[100:101], v[16:17] op_sel_hi:[1,0] neg_lo:[0,1] neg_hi:[0,1]
	v_pk_mul_f32 v[100:101], v[100:101], v[214:215] op_sel_hi:[1,0]
	v_pk_fma_f32 v[100:101], v[224:225], v[100:101], v[136:137]
	v_pk_add_f32 v[102:103], v[102:103], v[16:17] op_sel_hi:[1,0] neg_lo:[0,1] neg_hi:[0,1]
	v_pk_mul_f32 v[102:103], v[102:103], v[214:215] op_sel_hi:[1,0]
	v_pk_fma_f32 v[102:103], v[226:227], v[102:103], v[138:139]
	global_store_dwordx4 v[160:161], v[100:103], off nt
	v_pk_add_f32 v[96:97], v[96:97], v[16:17] op_sel_hi:[1,0] neg_lo:[0,1] neg_hi:[0,1]
	v_pk_mul_f32 v[96:97], v[96:97], v[214:215] op_sel_hi:[1,0]
	v_pk_fma_f32 v[96:97], v[228:229], v[96:97], v[140:141]
	v_pk_add_f32 v[98:99], v[98:99], v[16:17] op_sel_hi:[1,0] neg_lo:[0,1] neg_hi:[0,1]
	v_pk_mul_f32 v[98:99], v[98:99], v[214:215] op_sel_hi:[1,0]
	v_pk_fma_f32 v[98:99], v[230:231], v[98:99], v[142:143]
	global_store_dwordx4 v[160:161], v[96:99], off offset:64 nt
	v_pk_add_f32 v[28:29], v[28:29], v[16:17] op_sel_hi:[1,0] neg_lo:[0,1] neg_hi:[0,1]
	v_pk_mul_f32 v[28:29], v[28:29], v[214:215] op_sel_hi:[1,0]
	v_pk_fma_f32 v[28:29], v[232:233], v[28:29], v[144:145]
	v_pk_add_f32 v[30:31], v[30:31], v[16:17] op_sel_hi:[1,0] neg_lo:[0,1] neg_hi:[0,1]
	v_pk_mul_f32 v[30:31], v[30:31], v[214:215] op_sel_hi:[1,0]
	v_pk_fma_f32 v[30:31], v[234:235], v[30:31], v[146:147]
	global_store_dwordx4 v[160:161], v[28:31], off offset:512 nt
	v_pk_add_f32 v[24:25], v[24:25], v[16:17] op_sel_hi:[1,0] neg_lo:[0,1] neg_hi:[0,1]
	v_pk_mul_f32 v[24:25], v[24:25], v[214:215] op_sel_hi:[1,0]
	v_pk_fma_f32 v[24:25], v[236:237], v[24:25], v[148:149]
	v_pk_add_f32 v[26:27], v[26:27], v[16:17] op_sel_hi:[1,0] neg_lo:[0,1] neg_hi:[0,1]
	v_pk_mul_f32 v[26:27], v[26:27], v[214:215] op_sel_hi:[1,0]
	v_pk_fma_f32 v[26:27], v[238:239], v[26:27], v[150:151]
	global_store_dwordx4 v[160:161], v[24:27], off offset:576 nt
	v_add_u32_e32 v159, 0x2800, v156
	global_load_dwordx4 v[198:201], v159, s[10:11]
	global_load_dwordx4 v[202:205], v159, s[10:11] offset:16
	global_load_dwordx4 v[206:209], v159, s[10:11] offset:32
	global_load_dwordx4 v[210:213], v159, s[10:11] offset:48
	s_waitcnt vmcnt(8)
; __global__ void __launch_bounds__(512, 2) fwd_kernel(Args a) {
;     ...
;             for (int q = 0; q < 4; ++q) { float s2 = 0.f;
; #pragma unroll
;                 for (int j = 0; j < 8; ++j) { vr[q][j] = vr[q][j] - sm[q]; s2 += (vr[q][j][0] * vr[q][j][0] + vr[q][j][1] * vr[q][j][1]) + (vr[q][j][2] * vr[q][j][2] + vr[q][j][3] * vr[q][j][3]); }
;                 qq[q] = wave_sum(s2); rs[q] = 1.0f / sqrtf(qq[q] * (1.0f / DMODEL) + LN_EPS); }
; #pragma unroll
;             for (int q = 0; q < 4; ++q)
; #pragma unroll
;                 for (int j = 0; j < 8; ++j) __builtin_nontemporal_store(vr[q][j] * rs[q] * ggv[j] + bbv[j], xr + 512 * q + 64 * j); }
	v_add_f32_e32 v16, v0, v2
	v_add_f32_e32 v16, v16, v4
	v_add_f32_e32 v16, v16, v6
	v_add_f32_e32 v16, v16, v8
	v_add_f32_e32 v16, v16, v10
	v_add_f32_e32 v16, v16, v12
	v_add_f32_e32 v16, v16, v14
	v_mul_f32_e32 v16, 0x3a000000, v16
	v_add_f32_e32 v17, v1, v3
	v_add_f32_e32 v17, v17, v5
	v_add_f32_e32 v17, v17, v7
	v_add_f32_e32 v17, v17, v9
	v_add_f32_e32 v17, v17, v11
	v_add_f32_e32 v17, v17, v13
	v_add_f32_e32 v17, v17, v15
	v_fma_f32 v18, v0, s9, -v16
	v_mul_f32_e32 v18, v18, v18
	v_fmac_f32_e32 v17, 0x43800000, v18
	v_fma_f32 v18, v2, s9, -v16
	v_mul_f32_e32 v18, v18, v18
	v_fmac_f32_e32 v17, 0x43800000, v18
	v_fma_f32 v18, v4, s9, -v16
	v_mul_f32_e32 v18, v18, v18
	v_fmac_f32_e32 v17, 0x43800000, v18
	v_fma_f32 v18, v6, s9, -v16
	v_mul_f32_e32 v18, v18, v18
	v_fmac_f32_e32 v17, 0x43800000, v18
	v_fma_f32 v18, v8, s9, -v16
	v_mul_f32_e32 v18, v18, v18
	v_fmac_f32_e32 v17, 0x43800000, v18
	v_fma_f32 v18, v10, s9, -v16
	v_mul_f32_e32 v18, v18, v18
	v_fmac_f32_e32 v17, 0x43800000, v18
	v_fma_f32 v18, v12, s9, -v16
	v_mul_f32_e32 v18, v18, v18
	v_fmac_f32_e32 v17, 0x43800000, v18
	v_fma_f32 v18, v14, s9, -v16
	v_mul_f32_e32 v18, v18, v18
	v_fmac_f32_e32 v17, 0x43800000, v18
	v_fmamk_f32 v17, v17, 0x3a000000, v157
	v_mul_f32_e32 v18, 0x4f800000, v17
	v_cmp_gt_f32_e32 vcc, s3, v17
	s_nop 1
	v_cndmask_b32_e32 v214, v17, v18, vcc
	v_sqrt_f32_e32 v215, v214
	s_nop 1
	v_add_u32_e32 v216, -1, v215
	v_fma_f32 v217, -v216, v215, v214
	v_cmp_ge_f32_e64 s[14:15], 0, v217
	v_add_u32_e32 v217, 1, v215
	v_fma_f32 v218, -v217, v215, v214
	s_nop 0
	v_cndmask_b32_e64 v216, v215, v216, s[14:15]
	v_cmp_lt_f32_e64 s[14:15], 0, v218
	s_nop 1
	v_cndmask_b32_e64 v216, v216, v217, s[14:15]
	v_mul_f32_e32 v217, 0x37800000, v216
	v_cndmask_b32_e32 v216, v216, v217, vcc
	v_cmp_class_f32_e32 vcc, v214, v158
	s_nop 1
	v_cndmask_b32_e32 v214, v216, v214, vcc
	v_div_scale_f32 v215, s[14:15], v214, v214, 1.0
	v_rcp_f32_e32 v216, v215
	s_nop 1
	v_fma_f32 v217, -v215, v216, 1.0
	v_fmac_f32_e32 v216, v217, v216
	v_div_scale_f32 v217, vcc, 1.0, v214, 1.0
	v_mul_f32_e32 v218, v217, v216
	v_fma_f32 v219, -v215, v218, v217
	v_fmac_f32_e32 v218, v219, v216
	v_fma_f32 v217, -v215, v218, v217
	s_nop 1
	v_div_fmas_f32 v215, v217, v216, v218
	v_div_fixup_f32 v214, v215, v214, 1.0
	s_mov_b64 s[12:13], 0x120000
	v_lshl_add_u64 v[160:161], v[152:153], 0, s[12:13]
	v_pk_add_f32 v[92:93], v[92:93], v[16:17] op_sel_hi:[1,0] neg_lo:[0,1] neg_hi:[0,1]
	v_pk_mul_f32 v[92:93], v[92:93], v[214:215] op_sel_hi:[1,0]
	v_pk_fma_f32 v[92:93], v[224:225], v[92:93], v[136:137]
	v_pk_add_f32 v[94:95], v[94:95], v[16:17] op_sel_hi:[1,0] neg_lo:[0,1] neg_hi:[0,1]
	v_pk_mul_f32 v[94:95], v[94:95], v[214:215] op_sel_hi:[1,0]
	v_pk_fma_f32 v[94:95], v[226:227], v[94:95], v[138:139]
	global_store_dwordx4 v[160:161], v[92:95], off nt
	v_pk_add_f32 v[88:89], v[88:89], v[16:17] op_sel_hi:[1,0] neg_lo:[0,1] neg_hi:[0,1]
	v_pk_mul_f32 v[88:89], v[88:89], v[214:215] op_sel_hi:[1,0]
	v_pk_fma_f32 v[88:89], v[228:229], v[88:89], v[140:141]
	v_pk_add_f32 v[90:91], v[90:91], v[16:17] op_sel_hi:[1,0] neg_lo:[0,1] neg_hi:[0,1]
	v_pk_mul_f32 v[90:91], v[90:91], v[214:215] op_sel_hi:[1,0]
	v_pk_fma_f32 v[90:91], v[230:231], v[90:91], v[142:143]
	global_store_dwordx4 v[160:161], v[88:91], off offset:64 nt
	v_pk_add_f32 v[20:21], v[20:21], v[16:17] op_sel_hi:[1,0] neg_lo:[0,1] neg_hi:[0,1]
	v_pk_mul_f32 v[20:21], v[20:21], v[214:215] op_sel_hi:[1,0]
	v_pk_fma_f32 v[20:21], v[232:233], v[20:21], v[144:145]
	v_pk_add_f32 v[22:23], v[22:23], v[16:17] op_sel_hi:[1,0] neg_lo:[0,1] neg_hi:[0,1]
	v_pk_mul_f32 v[22:23], v[22:23], v[214:215] op_sel_hi:[1,0]
	v_pk_fma_f32 v[22:23], v[234:235], v[22:23], v[146:147]
	global_store_dwordx4 v[160:161], v[20:23], off offset:512 nt
	v_pk_add_f32 v[192:193], v[192:193], v[16:17] op_sel_hi:[1,0] neg_lo:[0,1] neg_hi:[0,1]
	v_pk_mul_f32 v[192:193], v[192:193], v[214:215] op_sel_hi:[1,0]
	v_pk_fma_f32 v[192:193], v[236:237], v[192:193], v[148:149]
	v_pk_add_f32 v[194:195], v[194:195], v[16:17] op_sel_hi:[1,0] neg_lo:[0,1] neg_hi:[0,1]
	v_pk_mul_f32 v[194:195], v[194:195], v[214:215] op_sel_hi:[1,0]
	v_pk_fma_f32 v[194:195], v[238:239], v[194:195], v[150:151]
	global_store_dwordx4 v[160:161], v[192:195], off offset:576 nt
	v_add_u32_e32 v159, 0x2c00, v156
	global_load_dwordx4 v[0:3], v159, s[10:11]
	global_load_dwordx4 v[4:7], v159, s[10:11] offset:16
	global_load_dwordx4 v[8:11], v159, s[10:11] offset:32
	global_load_dwordx4 v[12:15], v159, s[10:11] offset:48
	s_waitcnt vmcnt(8)
; __global__ void __launch_bounds__(512, 2) fwd_kernel(Args a) {
;     ...
;             for (int q = 0; q < 4; ++q) { float s2 = 0.f;
; #pragma unroll
;                 for (int j = 0; j < 8; ++j) { vr[q][j] = vr[q][j] - sm[q]; s2 += (vr[q][j][0] * vr[q][j][0] + vr[q][j][1] * vr[q][j][1]) + (vr[q][j][2] * vr[q][j][2] + vr[q][j][3] * vr[q][j][3]); }
;                 qq[q] = wave_sum(s2); rs[q] = 1.0f / sqrtf(qq[q] * (1.0f / DMODEL) + LN_EPS); }
; #pragma unroll
;             for (int q = 0; q < 4; ++q)
; #pragma unroll
;                 for (int j = 0; j < 8; ++j) __builtin_nontemporal_store(vr[q][j] * rs[q] * ggv[j] + bbv[j], xr + 512 * q + 64 * j); }
	v_add_f32_e32 v16, v198, v200
	v_add_f32_e32 v16, v16, v202
	v_add_f32_e32 v16, v16, v204
	v_add_f32_e32 v16, v16, v206
	v_add_f32_e32 v16, v16, v208
	v_add_f32_e32 v16, v16, v210
	v_add_f32_e32 v16, v16, v212
	v_mul_f32_e32 v16, 0x3a000000, v16
	v_add_f32_e32 v17, v199, v201
	v_add_f32_e32 v17, v17, v203
	v_add_f32_e32 v17, v17, v205
	v_add_f32_e32 v17, v17, v207
	v_add_f32_e32 v17, v17, v209
	v_add_f32_e32 v17, v17, v211
	v_add_f32_e32 v17, v17, v213
	v_fma_f32 v18, v198, s9, -v16
	v_mul_f32_e32 v18, v18, v18
	v_fmac_f32_e32 v17, 0x43800000, v18
	v_fma_f32 v18, v200, s9, -v16
	v_mul_f32_e32 v18, v18, v18
	v_fmac_f32_e32 v17, 0x43800000, v18
	v_fma_f32 v18, v202, s9, -v16
	v_mul_f32_e32 v18, v18, v18
	v_fmac_f32_e32 v17, 0x43800000, v18
	v_fma_f32 v18, v204, s9, -v16
	v_mul_f32_e32 v18, v18, v18
	v_fmac_f32_e32 v17, 0x43800000, v18
	v_fma_f32 v18, v206, s9, -v16
	v_mul_f32_e32 v18, v18, v18
	v_fmac_f32_e32 v17, 0x43800000, v18
	v_fma_f32 v18, v208, s9, -v16
	v_mul_f32_e32 v18, v18, v18
	v_fmac_f32_e32 v17, 0x43800000, v18
	v_fma_f32 v18, v210, s9, -v16
	v_mul_f32_e32 v18, v18, v18
	v_fmac_f32_e32 v17, 0x43800000, v18
	v_fma_f32 v18, v212, s9, -v16
	v_mul_f32_e32 v18, v18, v18
	v_fmac_f32_e32 v17, 0x43800000, v18
	v_fmamk_f32 v17, v17, 0x3a000000, v157
	v_mul_f32_e32 v18, 0x4f800000, v17
	v_cmp_gt_f32_e32 vcc, s3, v17
	s_nop 1
	v_cndmask_b32_e32 v214, v17, v18, vcc
	v_sqrt_f32_e32 v215, v214
	s_nop 1
	v_add_u32_e32 v216, -1, v215
	v_fma_f32 v217, -v216, v215, v214
	v_cmp_ge_f32_e64 s[14:15], 0, v217
	v_add_u32_e32 v217, 1, v215
	v_fma_f32 v218, -v217, v215, v214
	s_nop 0
	v_cndmask_b32_e64 v216, v215, v216, s[14:15]
	v_cmp_lt_f32_e64 s[14:15], 0, v218
	s_nop 1
	v_cndmask_b32_e64 v216, v216, v217, s[14:15]
	v_mul_f32_e32 v217, 0x37800000, v216
	v_cndmask_b32_e32 v216, v216, v217, vcc
	v_cmp_class_f32_e32 vcc, v214, v158
	s_nop 1
	v_cndmask_b32_e32 v214, v216, v214, vcc
	v_div_scale_f32 v215, s[14:15], v214, v214, 1.0
	v_rcp_f32_e32 v216, v215
	s_nop 1
	v_fma_f32 v217, -v215, v216, 1.0
	v_fmac_f32_e32 v216, v217, v216
	v_div_scale_f32 v217, vcc, 1.0, v214, 1.0
	v_mul_f32_e32 v218, v217, v216
	v_fma_f32 v219, -v215, v218, v217
	v_fmac_f32_e32 v218, v219, v216
	v_fma_f32 v217, -v215, v218, v217
	s_nop 1
	v_div_fmas_f32 v215, v217, v216, v218
	v_div_fixup_f32 v214, v215, v214, 1.0
	s_mov_b64 s[12:13], 0x140000
	v_lshl_add_u64 v[160:161], v[152:153], 0, s[12:13]
	v_pk_add_f32 v[84:85], v[84:85], v[16:17] op_sel_hi:[1,0] neg_lo:[0,1] neg_hi:[0,1]
	v_pk_mul_f32 v[84:85], v[84:85], v[214:215] op_sel_hi:[1,0]
	v_pk_fma_f32 v[84:85], v[224:225], v[84:85], v[136:137]
	v_pk_add_f32 v[86:87], v[86:87], v[16:17] op_sel_hi:[1,0] neg_lo:[0,1] neg_hi:[0,1]
	v_pk_mul_f32 v[86:87], v[86:87], v[214:215] op_sel_hi:[1,0]
	v_pk_fma_f32 v[86:87], v[226:227], v[86:87], v[138:139]
	global_store_dwordx4 v[160:161], v[84:87], off nt
	v_pk_add_f32 v[80:81], v[80:81], v[16:17] op_sel_hi:[1,0] neg_lo:[0,1] neg_hi:[0,1]
	v_pk_mul_f32 v[80:81], v[80:81], v[214:215] op_sel_hi:[1,0]
	v_pk_fma_f32 v[80:81], v[228:229], v[80:81], v[140:141]
	v_pk_add_f32 v[82:83], v[82:83], v[16:17] op_sel_hi:[1,0] neg_lo:[0,1] neg_hi:[0,1]
	v_pk_mul_f32 v[82:83], v[82:83], v[214:215] op_sel_hi:[1,0]
	v_pk_fma_f32 v[82:83], v[230:231], v[82:83], v[142:143]
	global_store_dwordx4 v[160:161], v[80:83], off offset:64 nt
	v_pk_add_f32 v[188:189], v[188:189], v[16:17] op_sel_hi:[1,0] neg_lo:[0,1] neg_hi:[0,1]
	v_pk_mul_f32 v[188:189], v[188:189], v[214:215] op_sel_hi:[1,0]
	v_pk_fma_f32 v[188:189], v[232:233], v[188:189], v[144:145]
	v_pk_add_f32 v[190:191], v[190:191], v[16:17] op_sel_hi:[1,0] neg_lo:[0,1] neg_hi:[0,1]
	v_pk_mul_f32 v[190:191], v[190:191], v[214:215] op_sel_hi:[1,0]
	v_pk_fma_f32 v[190:191], v[234:235], v[190:191], v[146:147]
	global_store_dwordx4 v[160:161], v[188:191], off offset:512 nt
	v_pk_add_f32 v[184:185], v[184:185], v[16:17] op_sel_hi:[1,0] neg_lo:[0,1] neg_hi:[0,1]
	v_pk_mul_f32 v[184:185], v[184:185], v[214:215] op_sel_hi:[1,0]
	v_pk_fma_f32 v[184:185], v[236:237], v[184:185], v[148:149]
	v_pk_add_f32 v[186:187], v[186:187], v[16:17] op_sel_hi:[1,0] neg_lo:[0,1] neg_hi:[0,1]
	v_pk_mul_f32 v[186:187], v[186:187], v[214:215] op_sel_hi:[1,0]
	v_pk_fma_f32 v[186:187], v[238:239], v[186:187], v[150:151]
	global_store_dwordx4 v[160:161], v[184:187], off offset:576 nt
	s_waitcnt vmcnt(4)
; __global__ void __launch_bounds__(512, 2) fwd_kernel(Args a) {
;     ...
;             for (int q = 0; q < 4; ++q) { float s_ = 0.f;
; #pragma unroll
;                 for (int j = 0; j < 8; ++j) s_ += (vr[q][j][0] + vr[q][j][1]) + (vr[q][j][2] + vr[q][j][3]);
;                 sm[q] = wave_sum(s_) * (1.0f / DMODEL); }
; #pragma unroll
;             for (int q = 0; q < 4; ++q) { float s2 = 0.f;
; #pragma unroll
;                 for (int j = 0; j < 8; ++j) { vr[q][j] = vr[q][j] - sm[q]; s2 += (vr[q][j][0] * vr[q][j][0] + vr[q][j][1] * vr[q][j][1]) + (vr[q][j][2] * vr[q][j][2] + vr[q][j][3] * vr[q][j][3]); }
;                 qq[q] = wave_sum(s2); rs[q] = 1.0f / sqrtf(qq[q] * (1.0f / DMODEL) + LN_EPS); }
; #pragma unroll
;             for (int q = 0; q < 4; ++q)
; #pragma unroll
;                 for (int j = 0; j < 8; ++j) __builtin_nontemporal_store(vr[q][j] * rs[q] * ggv[j] + bbv[j], xr + 512 * q + 64 * j); }
	v_add_f32_e32 v16, v0, v2
	v_add_f32_e32 v16, v16, v4
	v_add_f32_e32 v16, v16, v6
	v_add_f32_e32 v16, v16, v8
	v_add_f32_e32 v16, v16, v10
	v_add_f32_e32 v16, v16, v12
	v_add_f32_e32 v16, v16, v14
	v_mul_f32_e32 v16, 0x3a000000, v16
	v_add_f32_e32 v17, v1, v3
	v_add_f32_e32 v17, v17, v5
	v_add_f32_e32 v17, v17, v7
	v_add_f32_e32 v17, v17, v9
	v_add_f32_e32 v17, v17, v11
	v_add_f32_e32 v17, v17, v13
	v_add_f32_e32 v17, v17, v15
	v_fma_f32 v18, v0, s9, -v16
	v_mul_f32_e32 v18, v18, v18
	v_fmac_f32_e32 v17, 0x43800000, v18
	v_fma_f32 v18, v2, s9, -v16
	v_mul_f32_e32 v18, v18, v18
	v_fmac_f32_e32 v17, 0x43800000, v18
	v_fma_f32 v18, v4, s9, -v16
	v_mul_f32_e32 v18, v18, v18
	v_fmac_f32_e32 v17, 0x43800000, v18
	v_fma_f32 v18, v6, s9, -v16
	v_mul_f32_e32 v18, v18, v18
	v_fmac_f32_e32 v17, 0x43800000, v18
	v_fma_f32 v18, v8, s9, -v16
	v_mul_f32_e32 v18, v18, v18
	v_fmac_f32_e32 v17, 0x43800000, v18
	v_fma_f32 v18, v10, s9, -v16
	v_mul_f32_e32 v18, v18, v18
	v_fmac_f32_e32 v17, 0x43800000, v18
	v_fma_f32 v18, v12, s9, -v16
	v_mul_f32_e32 v18, v18, v18
	v_fmac_f32_e32 v17, 0x43800000, v18
	v_fma_f32 v18, v14, s9, -v16
	v_mul_f32_e32 v18, v18, v18
	v_fmac_f32_e32 v17, 0x43800000, v18
	v_fmamk_f32 v17, v17, 0x3a000000, v157
	v_mul_f32_e32 v18, 0x4f800000, v17
	v_cmp_gt_f32_e32 vcc, s3, v17
	s_nop 1
	v_cndmask_b32_e32 v214, v17, v18, vcc
	v_sqrt_f32_e32 v215, v214
	s_nop 1
	v_add_u32_e32 v216, -1, v215
	v_fma_f32 v217, -v216, v215, v214
	v_cmp_ge_f32_e64 s[14:15], 0, v217
	v_add_u32_e32 v217, 1, v215
	v_fma_f32 v218, -v217, v215, v214
	s_nop 0
	v_cndmask_b32_e64 v216, v215, v216, s[14:15]
	v_cmp_lt_f32_e64 s[14:15], 0, v218
	s_nop 1
	v_cndmask_b32_e64 v216, v216, v217, s[14:15]
	v_mul_f32_e32 v217, 0x37800000, v216
	v_cndmask_b32_e32 v216, v216, v217, vcc
	v_cmp_class_f32_e32 vcc, v214, v158
	s_nop 1
	v_cndmask_b32_e32 v214, v216, v214, vcc
	v_div_scale_f32 v215, s[14:15], v214, v214, 1.0
	v_rcp_f32_e32 v216, v215
	s_nop 1
	v_fma_f32 v217, -v215, v216, 1.0
	v_fmac_f32_e32 v216, v217, v216
	v_div_scale_f32 v217, vcc, 1.0, v214, 1.0
	v_mul_f32_e32 v218, v217, v216
	v_fma_f32 v219, -v215, v218, v217
	v_fmac_f32_e32 v218, v219, v216
	v_fma_f32 v217, -v215, v218, v217
	s_nop 1
	v_div_fmas_f32 v215, v217, v216, v218
	v_div_fixup_f32 v214, v215, v214, 1.0
	s_mov_b64 s[12:13], 0x160000
	v_lshl_add_u64 v[160:161], v[152:153], 0, s[12:13]
	v_pk_add_f32 v[76:77], v[76:77], v[16:17] op_sel_hi:[1,0] neg_lo:[0,1] neg_hi:[0,1]
	v_pk_mul_f32 v[76:77], v[76:77], v[214:215] op_sel_hi:[1,0]
	v_pk_fma_f32 v[76:77], v[224:225], v[76:77], v[136:137]
	v_pk_add_f32 v[78:79], v[78:79], v[16:17] op_sel_hi:[1,0] neg_lo:[0,1] neg_hi:[0,1]
	v_pk_mul_f32 v[78:79], v[78:79], v[214:215] op_sel_hi:[1,0]
	v_pk_fma_f32 v[78:79], v[226:227], v[78:79], v[138:139]
	global_store_dwordx4 v[160:161], v[76:79], off nt
	v_pk_add_f32 v[72:73], v[72:73], v[16:17] op_sel_hi:[1,0] neg_lo:[0,1] neg_hi:[0,1]
	v_pk_mul_f32 v[72:73], v[72:73], v[214:215] op_sel_hi:[1,0]
	v_pk_fma_f32 v[72:73], v[228:229], v[72:73], v[140:141]
	v_pk_add_f32 v[74:75], v[74:75], v[16:17] op_sel_hi:[1,0] neg_lo:[0,1] neg_hi:[0,1]
	v_pk_mul_f32 v[74:75], v[74:75], v[214:215] op_sel_hi:[1,0]
	v_pk_fma_f32 v[74:75], v[230:231], v[74:75], v[142:143]
	global_store_dwordx4 v[160:161], v[72:75], off offset:64 nt
	v_pk_add_f32 v[180:181], v[180:181], v[16:17] op_sel_hi:[1,0] neg_lo:[0,1] neg_hi:[0,1]
	v_pk_mul_f32 v[180:181], v[180:181], v[214:215] op_sel_hi:[1,0]
	v_pk_fma_f32 v[180:181], v[232:233], v[180:181], v[144:145]
	v_pk_add_f32 v[182:183], v[182:183], v[16:17] op_sel_hi:[1,0] neg_lo:[0,1] neg_hi:[0,1]
	v_pk_mul_f32 v[182:183], v[182:183], v[214:215] op_sel_hi:[1,0]
	v_pk_fma_f32 v[182:183], v[234:235], v[182:183], v[146:147]
	global_store_dwordx4 v[160:161], v[180:183], off offset:512 nt
	v_pk_add_f32 v[176:177], v[176:177], v[16:17] op_sel_hi:[1,0] neg_lo:[0,1] neg_hi:[0,1]
	v_pk_mul_f32 v[176:177], v[176:177], v[214:215] op_sel_hi:[1,0]
	v_pk_fma_f32 v[176:177], v[236:237], v[176:177], v[148:149]
	v_pk_add_f32 v[178:179], v[178:179], v[16:17] op_sel_hi:[1,0] neg_lo:[0,1] neg_hi:[0,1]
	v_pk_mul_f32 v[178:179], v[178:179], v[214:215] op_sel_hi:[1,0]
	v_pk_fma_f32 v[178:179], v[238:239], v[178:179], v[150:151]
	global_store_dwordx4 v[160:161], v[176:179], off offset:576 nt
